# layer-0 inter-chunk state scan (phase 3) hand-written: loads run four 8-chunk groups ahead (compiled loop: one group ahead, latency-bound), SGPR chunk bases, scalar SSD decays, v_cvt_pk_bf16_f32 packi
# speedup vs baseline: 1.0144x; 1.0124x over previous
.LBB0_571:
	v_readlane_b32 s0, v253, 4
	s_cmp_lt_i32 s0, 4
	s_cbranch_scc1 .LBB0_638
	s_mov_b64 s[6:7], exec
	s_load_dwordx4 s[8:11], s[92:93], 0x110
	v_readfirstlane_b32 s12, v162
	v_and_b32_e32 v1, 0xffff, v162
	s_lshr_b32 s13, s12, 16
	s_and_b32 s14, s12, 0xffff
	s_lshl_b32 s15, s13, 25
	s_waitcnt lgkmcnt(0)
	s_cmp_lt_u32 s14, 0x8000
	s_cbranch_scc0 .Lp3_ssd
	s_add_u32 s16, s8, s15
	s_addc_u32 s17, s9, 0
	s_mov_b64 s[18:19], s[16:17]
	v_lshlrev_b32_e32 v2, 2, v1
	s_lshr_b32 s20, s14, 13
	v_cvt_f32_u32_e32 v3, s20
	v_sub_f32_e32 v3, 0xc0a00000, v3
	v_exp_f32_e32 v3, v3
	s_nop 0
	v_sub_f32_e32 v3, 1.0, v3
	v_log_f32_e32 v3, v3
	s_nop 0
	v_mul_f32_e32 v3, 0x42800000, v3
	v_exp_f32_e32 v3, v3
	s_nop 1
	v_readfirstlane_b32 s21, v3
	v_mov_b32_e32 v4, 0
	v_mov_b32_e32 v5, 0
	global_load_dword v8, v2, s[16:17]
	s_add_u32 s16, s16, 0x20000
	s_addc_u32 s17, s17, 0
	global_load_dword v9, v2, s[16:17]
	s_add_u32 s16, s16, 0x20000
	s_addc_u32 s17, s17, 0
	global_load_dword v10, v2, s[16:17]
	s_add_u32 s16, s16, 0x20000
	s_addc_u32 s17, s17, 0
	global_load_dword v11, v2, s[16:17]
	s_add_u32 s16, s16, 0x20000
	s_addc_u32 s17, s17, 0
	global_load_dword v12, v2, s[16:17]
	s_add_u32 s16, s16, 0x20000
	s_addc_u32 s17, s17, 0
	global_load_dword v13, v2, s[16:17]
	s_add_u32 s16, s16, 0x20000
	s_addc_u32 s17, s17, 0
	global_load_dword v14, v2, s[16:17]
	s_add_u32 s16, s16, 0x20000
	s_addc_u32 s17, s17, 0
	global_load_dword v15, v2, s[16:17]
	s_add_u32 s16, s16, 0x20000
	s_addc_u32 s17, s17, 0
	global_load_dword v16, v2, s[16:17]
	s_add_u32 s16, s16, 0x20000
	s_addc_u32 s17, s17, 0
	global_load_dword v17, v2, s[16:17]
	s_add_u32 s16, s16, 0x20000
	s_addc_u32 s17, s17, 0
	global_load_dword v18, v2, s[16:17]
	s_add_u32 s16, s16, 0x20000
	s_addc_u32 s17, s17, 0
	global_load_dword v19, v2, s[16:17]
	s_add_u32 s16, s16, 0x20000
	s_addc_u32 s17, s17, 0
	global_load_dword v20, v2, s[16:17]
	s_add_u32 s16, s16, 0x20000
	s_addc_u32 s17, s17, 0
	global_load_dword v21, v2, s[16:17]
	s_add_u32 s16, s16, 0x20000
	s_addc_u32 s17, s17, 0
	global_load_dword v22, v2, s[16:17]
	s_add_u32 s16, s16, 0x20000
	s_addc_u32 s17, s17, 0
	global_load_dword v23, v2, s[16:17]
	s_add_u32 s16, s16, 0x20000
	s_addc_u32 s17, s17, 0
	global_load_dword v24, v2, s[16:17]
	s_add_u32 s16, s16, 0x20000
	s_addc_u32 s17, s17, 0
	global_load_dword v25, v2, s[16:17]
	s_add_u32 s16, s16, 0x20000
	s_addc_u32 s17, s17, 0
	global_load_dword v26, v2, s[16:17]
	s_add_u32 s16, s16, 0x20000
	s_addc_u32 s17, s17, 0
	global_load_dword v27, v2, s[16:17]
	s_add_u32 s16, s16, 0x20000
	s_addc_u32 s17, s17, 0
	global_load_dword v28, v2, s[16:17]
	s_add_u32 s16, s16, 0x20000
	s_addc_u32 s17, s17, 0
	global_load_dword v29, v2, s[16:17]
	s_add_u32 s16, s16, 0x20000
	s_addc_u32 s17, s17, 0
	global_load_dword v30, v2, s[16:17]
	s_add_u32 s16, s16, 0x20000
	s_addc_u32 s17, s17, 0
	global_load_dword v31, v2, s[16:17]
	s_add_u32 s16, s16, 0x20000
	s_addc_u32 s17, s17, 0
	global_load_dword v32, v2, s[16:17]
	s_add_u32 s16, s16, 0x20000
	s_addc_u32 s17, s17, 0
	global_load_dword v33, v2, s[16:17]
	s_add_u32 s16, s16, 0x20000
	s_addc_u32 s17, s17, 0
	global_load_dword v34, v2, s[16:17]
	s_add_u32 s16, s16, 0x20000
	s_addc_u32 s17, s17, 0
	global_load_dword v35, v2, s[16:17]
	s_add_u32 s16, s16, 0x20000
	s_addc_u32 s17, s17, 0
	global_load_dword v36, v2, s[16:17]
	s_add_u32 s16, s16, 0x20000
	s_addc_u32 s17, s17, 0
	global_load_dword v37, v2, s[16:17]
	s_add_u32 s16, s16, 0x20000
	s_addc_u32 s17, s17, 0
	global_load_dword v38, v2, s[16:17]
	s_add_u32 s16, s16, 0x20000
	s_addc_u32 s17, s17, 0
	global_load_dword v39, v2, s[16:17]
	s_add_u32 s16, s16, 0x20000
	s_addc_u32 s17, s17, 0
	s_waitcnt vmcnt(24)
	v_cvt_pk_bf16_f32 v6, v4, v5
	global_store_dword v2, v6, s[18:19]
	s_add_u32 s18, s18, 0x20000
	s_addc_u32 s19, s19, 0
	v_lshlrev_b32_e32 v40, 16, v8
	v_and_b32_e32 v41, 0xffff0000, v8
	v_fma_f32 v4, v4, s21, v40
	v_fma_f32 v5, v5, s21, v41
	v_cvt_pk_bf16_f32 v6, v4, v5
	global_store_dword v2, v6, s[18:19]
	s_add_u32 s18, s18, 0x20000
	s_addc_u32 s19, s19, 0
	v_lshlrev_b32_e32 v40, 16, v9
	v_and_b32_e32 v41, 0xffff0000, v9
	v_fma_f32 v4, v4, s21, v40
	v_fma_f32 v5, v5, s21, v41
	v_cvt_pk_bf16_f32 v6, v4, v5
	global_store_dword v2, v6, s[18:19]
	s_add_u32 s18, s18, 0x20000
	s_addc_u32 s19, s19, 0
	v_lshlrev_b32_e32 v40, 16, v10
	v_and_b32_e32 v41, 0xffff0000, v10
	v_fma_f32 v4, v4, s21, v40
	v_fma_f32 v5, v5, s21, v41
	v_cvt_pk_bf16_f32 v6, v4, v5
	global_store_dword v2, v6, s[18:19]
	s_add_u32 s18, s18, 0x20000
	s_addc_u32 s19, s19, 0
	v_lshlrev_b32_e32 v40, 16, v11
	v_and_b32_e32 v41, 0xffff0000, v11
	v_fma_f32 v4, v4, s21, v40
	v_fma_f32 v5, v5, s21, v41
	v_cvt_pk_bf16_f32 v6, v4, v5
	global_store_dword v2, v6, s[18:19]
	s_add_u32 s18, s18, 0x20000
	s_addc_u32 s19, s19, 0
	v_lshlrev_b32_e32 v40, 16, v12
	v_and_b32_e32 v41, 0xffff0000, v12
	v_fma_f32 v4, v4, s21, v40
	v_fma_f32 v5, v5, s21, v41
	v_cvt_pk_bf16_f32 v6, v4, v5
	global_store_dword v2, v6, s[18:19]
	s_add_u32 s18, s18, 0x20000
	s_addc_u32 s19, s19, 0
	v_lshlrev_b32_e32 v40, 16, v13
	v_and_b32_e32 v41, 0xffff0000, v13
	v_fma_f32 v4, v4, s21, v40
	v_fma_f32 v5, v5, s21, v41
	v_cvt_pk_bf16_f32 v6, v4, v5
	global_store_dword v2, v6, s[18:19]
	s_add_u32 s18, s18, 0x20000
	s_addc_u32 s19, s19, 0
	v_lshlrev_b32_e32 v40, 16, v14
	v_and_b32_e32 v41, 0xffff0000, v14
	v_fma_f32 v4, v4, s21, v40
	v_fma_f32 v5, v5, s21, v41
	v_cvt_pk_bf16_f32 v6, v4, v5
	global_store_dword v2, v6, s[18:19]
	s_add_u32 s18, s18, 0x20000
	s_addc_u32 s19, s19, 0
	v_lshlrev_b32_e32 v40, 16, v15
	v_and_b32_e32 v41, 0xffff0000, v15
	v_fma_f32 v4, v4, s21, v40
	v_fma_f32 v5, v5, s21, v41
	global_load_dword v8, v2, s[16:17]
	s_add_u32 s16, s16, 0x20000
	s_addc_u32 s17, s17, 0
	global_load_dword v9, v2, s[16:17]
	s_add_u32 s16, s16, 0x20000
	s_addc_u32 s17, s17, 0
	global_load_dword v10, v2, s[16:17]
	s_add_u32 s16, s16, 0x20000
	s_addc_u32 s17, s17, 0
	global_load_dword v11, v2, s[16:17]
	s_add_u32 s16, s16, 0x20000
	s_addc_u32 s17, s17, 0
	global_load_dword v12, v2, s[16:17]
	s_add_u32 s16, s16, 0x20000
	s_addc_u32 s17, s17, 0
	global_load_dword v13, v2, s[16:17]
	s_add_u32 s16, s16, 0x20000
	s_addc_u32 s17, s17, 0
	global_load_dword v14, v2, s[16:17]
	s_add_u32 s16, s16, 0x20000
	s_addc_u32 s17, s17, 0
	global_load_dword v15, v2, s[16:17]
	s_add_u32 s16, s16, 0x20000
	s_addc_u32 s17, s17, 0
	s_waitcnt vmcnt(32)
	v_cvt_pk_bf16_f32 v6, v4, v5
	global_store_dword v2, v6, s[18:19]
	s_add_u32 s18, s18, 0x20000
	s_addc_u32 s19, s19, 0
	v_lshlrev_b32_e32 v40, 16, v16
	v_and_b32_e32 v41, 0xffff0000, v16
	v_fma_f32 v4, v4, s21, v40
	v_fma_f32 v5, v5, s21, v41
	v_cvt_pk_bf16_f32 v6, v4, v5
	global_store_dword v2, v6, s[18:19]
	s_add_u32 s18, s18, 0x20000
	s_addc_u32 s19, s19, 0
	v_lshlrev_b32_e32 v40, 16, v17
	v_and_b32_e32 v41, 0xffff0000, v17
	v_fma_f32 v4, v4, s21, v40
	v_fma_f32 v5, v5, s21, v41
	v_cvt_pk_bf16_f32 v6, v4, v5
	global_store_dword v2, v6, s[18:19]
	s_add_u32 s18, s18, 0x20000
	s_addc_u32 s19, s19, 0
	v_lshlrev_b32_e32 v40, 16, v18
	v_and_b32_e32 v41, 0xffff0000, v18
	v_fma_f32 v4, v4, s21, v40
	v_fma_f32 v5, v5, s21, v41
	v_cvt_pk_bf16_f32 v6, v4, v5
	global_store_dword v2, v6, s[18:19]
	s_add_u32 s18, s18, 0x20000
	s_addc_u32 s19, s19, 0
	v_lshlrev_b32_e32 v40, 16, v19
	v_and_b32_e32 v41, 0xffff0000, v19
	v_fma_f32 v4, v4, s21, v40
	v_fma_f32 v5, v5, s21, v41
	v_cvt_pk_bf16_f32 v6, v4, v5
	global_store_dword v2, v6, s[18:19]
	s_add_u32 s18, s18, 0x20000
	s_addc_u32 s19, s19, 0
	v_lshlrev_b32_e32 v40, 16, v20
	v_and_b32_e32 v41, 0xffff0000, v20
	v_fma_f32 v4, v4, s21, v40
	v_fma_f32 v5, v5, s21, v41
	v_cvt_pk_bf16_f32 v6, v4, v5
	global_store_dword v2, v6, s[18:19]
	s_add_u32 s18, s18, 0x20000
	s_addc_u32 s19, s19, 0
	v_lshlrev_b32_e32 v40, 16, v21
	v_and_b32_e32 v41, 0xffff0000, v21
	v_fma_f32 v4, v4, s21, v40
	v_fma_f32 v5, v5, s21, v41
	v_cvt_pk_bf16_f32 v6, v4, v5
	global_store_dword v2, v6, s[18:19]
	s_add_u32 s18, s18, 0x20000
	s_addc_u32 s19, s19, 0
	v_lshlrev_b32_e32 v40, 16, v22
	v_and_b32_e32 v41, 0xffff0000, v22
	v_fma_f32 v4, v4, s21, v40
	v_fma_f32 v5, v5, s21, v41
	v_cvt_pk_bf16_f32 v6, v4, v5
	global_store_dword v2, v6, s[18:19]
	s_add_u32 s18, s18, 0x20000
	s_addc_u32 s19, s19, 0
	v_lshlrev_b32_e32 v40, 16, v23
	v_and_b32_e32 v41, 0xffff0000, v23
	v_fma_f32 v4, v4, s21, v40
	v_fma_f32 v5, v5, s21, v41
	global_load_dword v16, v2, s[16:17]
	s_add_u32 s16, s16, 0x20000
	s_addc_u32 s17, s17, 0
	global_load_dword v17, v2, s[16:17]
	s_add_u32 s16, s16, 0x20000
	s_addc_u32 s17, s17, 0
	global_load_dword v18, v2, s[16:17]
	s_add_u32 s16, s16, 0x20000
	s_addc_u32 s17, s17, 0
	global_load_dword v19, v2, s[16:17]
	s_add_u32 s16, s16, 0x20000
	s_addc_u32 s17, s17, 0
	global_load_dword v20, v2, s[16:17]
	s_add_u32 s16, s16, 0x20000
	s_addc_u32 s17, s17, 0
	global_load_dword v21, v2, s[16:17]
	s_add_u32 s16, s16, 0x20000
	s_addc_u32 s17, s17, 0
	global_load_dword v22, v2, s[16:17]
	s_add_u32 s16, s16, 0x20000
	s_addc_u32 s17, s17, 0
	global_load_dword v23, v2, s[16:17]
	s_add_u32 s16, s16, 0x20000
	s_addc_u32 s17, s17, 0
	s_waitcnt vmcnt(40)
	v_cvt_pk_bf16_f32 v6, v4, v5
	global_store_dword v2, v6, s[18:19]
	s_add_u32 s18, s18, 0x20000
	s_addc_u32 s19, s19, 0
	v_lshlrev_b32_e32 v40, 16, v24
	v_and_b32_e32 v41, 0xffff0000, v24
	v_fma_f32 v4, v4, s21, v40
	v_fma_f32 v5, v5, s21, v41
	v_cvt_pk_bf16_f32 v6, v4, v5
	global_store_dword v2, v6, s[18:19]
	s_add_u32 s18, s18, 0x20000
	s_addc_u32 s19, s19, 0
	v_lshlrev_b32_e32 v40, 16, v25
	v_and_b32_e32 v41, 0xffff0000, v25
	v_fma_f32 v4, v4, s21, v40
	v_fma_f32 v5, v5, s21, v41
	v_cvt_pk_bf16_f32 v6, v4, v5
	global_store_dword v2, v6, s[18:19]
	s_add_u32 s18, s18, 0x20000
	s_addc_u32 s19, s19, 0
	v_lshlrev_b32_e32 v40, 16, v26
	v_and_b32_e32 v41, 0xffff0000, v26
	v_fma_f32 v4, v4, s21, v40
	v_fma_f32 v5, v5, s21, v41
	v_cvt_pk_bf16_f32 v6, v4, v5
	global_store_dword v2, v6, s[18:19]
	s_add_u32 s18, s18, 0x20000
	s_addc_u32 s19, s19, 0
	v_lshlrev_b32_e32 v40, 16, v27
	v_and_b32_e32 v41, 0xffff0000, v27
	v_fma_f32 v4, v4, s21, v40
	v_fma_f32 v5, v5, s21, v41
	v_cvt_pk_bf16_f32 v6, v4, v5
	global_store_dword v2, v6, s[18:19]
	s_add_u32 s18, s18, 0x20000
	s_addc_u32 s19, s19, 0
	v_lshlrev_b32_e32 v40, 16, v28
	v_and_b32_e32 v41, 0xffff0000, v28
	v_fma_f32 v4, v4, s21, v40
	v_fma_f32 v5, v5, s21, v41
	v_cvt_pk_bf16_f32 v6, v4, v5
	global_store_dword v2, v6, s[18:19]
	s_add_u32 s18, s18, 0x20000
	s_addc_u32 s19, s19, 0
	v_lshlrev_b32_e32 v40, 16, v29
	v_and_b32_e32 v41, 0xffff0000, v29
	v_fma_f32 v4, v4, s21, v40
	v_fma_f32 v5, v5, s21, v41
	v_cvt_pk_bf16_f32 v6, v4, v5
	global_store_dword v2, v6, s[18:19]
	s_add_u32 s18, s18, 0x20000
	s_addc_u32 s19, s19, 0
	v_lshlrev_b32_e32 v40, 16, v30
	v_and_b32_e32 v41, 0xffff0000, v30
	v_fma_f32 v4, v4, s21, v40
	v_fma_f32 v5, v5, s21, v41
	v_cvt_pk_bf16_f32 v6, v4, v5
	global_store_dword v2, v6, s[18:19]
	s_add_u32 s18, s18, 0x20000
	s_addc_u32 s19, s19, 0
	v_lshlrev_b32_e32 v40, 16, v31
	v_and_b32_e32 v41, 0xffff0000, v31
	v_fma_f32 v4, v4, s21, v40
	v_fma_f32 v5, v5, s21, v41
	global_load_dword v24, v2, s[16:17]
	s_add_u32 s16, s16, 0x20000
	s_addc_u32 s17, s17, 0
	global_load_dword v25, v2, s[16:17]
	s_add_u32 s16, s16, 0x20000
	s_addc_u32 s17, s17, 0
	global_load_dword v26, v2, s[16:17]
	s_add_u32 s16, s16, 0x20000
	s_addc_u32 s17, s17, 0
	global_load_dword v27, v2, s[16:17]
	s_add_u32 s16, s16, 0x20000
	s_addc_u32 s17, s17, 0
	global_load_dword v28, v2, s[16:17]
	s_add_u32 s16, s16, 0x20000
	s_addc_u32 s17, s17, 0
	global_load_dword v29, v2, s[16:17]
	s_add_u32 s16, s16, 0x20000
	s_addc_u32 s17, s17, 0
	global_load_dword v30, v2, s[16:17]
	s_add_u32 s16, s16, 0x20000
	s_addc_u32 s17, s17, 0
	global_load_dword v31, v2, s[16:17]
	s_add_u32 s16, s16, 0x20000
	s_addc_u32 s17, s17, 0
	s_waitcnt vmcnt(48)
	v_cvt_pk_bf16_f32 v6, v4, v5
	global_store_dword v2, v6, s[18:19]
	s_add_u32 s18, s18, 0x20000
	s_addc_u32 s19, s19, 0
	v_lshlrev_b32_e32 v40, 16, v32
	v_and_b32_e32 v41, 0xffff0000, v32
	v_fma_f32 v4, v4, s21, v40
	v_fma_f32 v5, v5, s21, v41
	v_cvt_pk_bf16_f32 v6, v4, v5
	global_store_dword v2, v6, s[18:19]
	s_add_u32 s18, s18, 0x20000
	s_addc_u32 s19, s19, 0
	v_lshlrev_b32_e32 v40, 16, v33
	v_and_b32_e32 v41, 0xffff0000, v33
	v_fma_f32 v4, v4, s21, v40
	v_fma_f32 v5, v5, s21, v41
	v_cvt_pk_bf16_f32 v6, v4, v5
	global_store_dword v2, v6, s[18:19]
	s_add_u32 s18, s18, 0x20000
	s_addc_u32 s19, s19, 0
	v_lshlrev_b32_e32 v40, 16, v34
	v_and_b32_e32 v41, 0xffff0000, v34
	v_fma_f32 v4, v4, s21, v40
	v_fma_f32 v5, v5, s21, v41
	v_cvt_pk_bf16_f32 v6, v4, v5
	global_store_dword v2, v6, s[18:19]
	s_add_u32 s18, s18, 0x20000
	s_addc_u32 s19, s19, 0
	v_lshlrev_b32_e32 v40, 16, v35
	v_and_b32_e32 v41, 0xffff0000, v35
	v_fma_f32 v4, v4, s21, v40
	v_fma_f32 v5, v5, s21, v41
	v_cvt_pk_bf16_f32 v6, v4, v5
	global_store_dword v2, v6, s[18:19]
	s_add_u32 s18, s18, 0x20000
	s_addc_u32 s19, s19, 0
	v_lshlrev_b32_e32 v40, 16, v36
	v_and_b32_e32 v41, 0xffff0000, v36
	v_fma_f32 v4, v4, s21, v40
	v_fma_f32 v5, v5, s21, v41
	v_cvt_pk_bf16_f32 v6, v4, v5
	global_store_dword v2, v6, s[18:19]
	s_add_u32 s18, s18, 0x20000
	s_addc_u32 s19, s19, 0
	v_lshlrev_b32_e32 v40, 16, v37
	v_and_b32_e32 v41, 0xffff0000, v37
	v_fma_f32 v4, v4, s21, v40
	v_fma_f32 v5, v5, s21, v41
	v_cvt_pk_bf16_f32 v6, v4, v5
	global_store_dword v2, v6, s[18:19]
	s_add_u32 s18, s18, 0x20000
	s_addc_u32 s19, s19, 0
	v_lshlrev_b32_e32 v40, 16, v38
	v_and_b32_e32 v41, 0xffff0000, v38
	v_fma_f32 v4, v4, s21, v40
	v_fma_f32 v5, v5, s21, v41
	v_cvt_pk_bf16_f32 v6, v4, v5
	global_store_dword v2, v6, s[18:19]
	s_add_u32 s18, s18, 0x20000
	s_addc_u32 s19, s19, 0
	v_lshlrev_b32_e32 v40, 16, v39
	v_and_b32_e32 v41, 0xffff0000, v39
	v_fma_f32 v4, v4, s21, v40
	v_fma_f32 v5, v5, s21, v41
	global_load_dword v32, v2, s[16:17]
	s_add_u32 s16, s16, 0x20000
	s_addc_u32 s17, s17, 0
	global_load_dword v33, v2, s[16:17]
	s_add_u32 s16, s16, 0x20000
	s_addc_u32 s17, s17, 0
	global_load_dword v34, v2, s[16:17]
	s_add_u32 s16, s16, 0x20000
	s_addc_u32 s17, s17, 0
	global_load_dword v35, v2, s[16:17]
	s_add_u32 s16, s16, 0x20000
	s_addc_u32 s17, s17, 0
	global_load_dword v36, v2, s[16:17]
	s_add_u32 s16, s16, 0x20000
	s_addc_u32 s17, s17, 0
	global_load_dword v37, v2, s[16:17]
	s_add_u32 s16, s16, 0x20000
	s_addc_u32 s17, s17, 0
	global_load_dword v38, v2, s[16:17]
	s_add_u32 s16, s16, 0x20000
	s_addc_u32 s17, s17, 0
	global_load_dword v39, v2, s[16:17]
	s_add_u32 s16, s16, 0x20000
	s_addc_u32 s17, s17, 0
	s_mov_b32 s22, 6
.Lp3_ret_loop:
	s_waitcnt vmcnt(48)
	v_cvt_pk_bf16_f32 v6, v4, v5
	global_store_dword v2, v6, s[18:19]
	s_add_u32 s18, s18, 0x20000
	s_addc_u32 s19, s19, 0
	v_lshlrev_b32_e32 v40, 16, v8
	v_and_b32_e32 v41, 0xffff0000, v8
	v_fma_f32 v4, v4, s21, v40
	v_fma_f32 v5, v5, s21, v41
	v_cvt_pk_bf16_f32 v6, v4, v5
	global_store_dword v2, v6, s[18:19]
	s_add_u32 s18, s18, 0x20000
	s_addc_u32 s19, s19, 0
	v_lshlrev_b32_e32 v40, 16, v9
	v_and_b32_e32 v41, 0xffff0000, v9
	v_fma_f32 v4, v4, s21, v40
	v_fma_f32 v5, v5, s21, v41
	v_cvt_pk_bf16_f32 v6, v4, v5
	global_store_dword v2, v6, s[18:19]
	s_add_u32 s18, s18, 0x20000
	s_addc_u32 s19, s19, 0
	v_lshlrev_b32_e32 v40, 16, v10
	v_and_b32_e32 v41, 0xffff0000, v10
	v_fma_f32 v4, v4, s21, v40
	v_fma_f32 v5, v5, s21, v41
	v_cvt_pk_bf16_f32 v6, v4, v5
	global_store_dword v2, v6, s[18:19]
	s_add_u32 s18, s18, 0x20000
	s_addc_u32 s19, s19, 0
	v_lshlrev_b32_e32 v40, 16, v11
	v_and_b32_e32 v41, 0xffff0000, v11
	v_fma_f32 v4, v4, s21, v40
	v_fma_f32 v5, v5, s21, v41
	v_cvt_pk_bf16_f32 v6, v4, v5
	global_store_dword v2, v6, s[18:19]
	s_add_u32 s18, s18, 0x20000
	s_addc_u32 s19, s19, 0
	v_lshlrev_b32_e32 v40, 16, v12
	v_and_b32_e32 v41, 0xffff0000, v12
	v_fma_f32 v4, v4, s21, v40
	v_fma_f32 v5, v5, s21, v41
	v_cvt_pk_bf16_f32 v6, v4, v5
	global_store_dword v2, v6, s[18:19]
	s_add_u32 s18, s18, 0x20000
	s_addc_u32 s19, s19, 0
	v_lshlrev_b32_e32 v40, 16, v13
	v_and_b32_e32 v41, 0xffff0000, v13
	v_fma_f32 v4, v4, s21, v40
	v_fma_f32 v5, v5, s21, v41
	v_cvt_pk_bf16_f32 v6, v4, v5
	global_store_dword v2, v6, s[18:19]
	s_add_u32 s18, s18, 0x20000
	s_addc_u32 s19, s19, 0
	v_lshlrev_b32_e32 v40, 16, v14
	v_and_b32_e32 v41, 0xffff0000, v14
	v_fma_f32 v4, v4, s21, v40
	v_fma_f32 v5, v5, s21, v41
	v_cvt_pk_bf16_f32 v6, v4, v5
	global_store_dword v2, v6, s[18:19]
	s_add_u32 s18, s18, 0x20000
	s_addc_u32 s19, s19, 0
	v_lshlrev_b32_e32 v40, 16, v15
	v_and_b32_e32 v41, 0xffff0000, v15
	v_fma_f32 v4, v4, s21, v40
	v_fma_f32 v5, v5, s21, v41
	global_load_dword v8, v2, s[16:17]
	s_add_u32 s16, s16, 0x20000
	s_addc_u32 s17, s17, 0
	global_load_dword v9, v2, s[16:17]
	s_add_u32 s16, s16, 0x20000
	s_addc_u32 s17, s17, 0
	global_load_dword v10, v2, s[16:17]
	s_add_u32 s16, s16, 0x20000
	s_addc_u32 s17, s17, 0
	global_load_dword v11, v2, s[16:17]
	s_add_u32 s16, s16, 0x20000
	s_addc_u32 s17, s17, 0
	global_load_dword v12, v2, s[16:17]
	s_add_u32 s16, s16, 0x20000
	s_addc_u32 s17, s17, 0
	global_load_dword v13, v2, s[16:17]
	s_add_u32 s16, s16, 0x20000
	s_addc_u32 s17, s17, 0
	global_load_dword v14, v2, s[16:17]
	s_add_u32 s16, s16, 0x20000
	s_addc_u32 s17, s17, 0
	global_load_dword v15, v2, s[16:17]
	s_add_u32 s16, s16, 0x20000
	s_addc_u32 s17, s17, 0
	s_waitcnt vmcnt(48)
	v_cvt_pk_bf16_f32 v6, v4, v5
	global_store_dword v2, v6, s[18:19]
	s_add_u32 s18, s18, 0x20000
	s_addc_u32 s19, s19, 0
	v_lshlrev_b32_e32 v40, 16, v16
	v_and_b32_e32 v41, 0xffff0000, v16
	v_fma_f32 v4, v4, s21, v40
	v_fma_f32 v5, v5, s21, v41
	v_cvt_pk_bf16_f32 v6, v4, v5
	global_store_dword v2, v6, s[18:19]
	s_add_u32 s18, s18, 0x20000
	s_addc_u32 s19, s19, 0
	v_lshlrev_b32_e32 v40, 16, v17
	v_and_b32_e32 v41, 0xffff0000, v17
	v_fma_f32 v4, v4, s21, v40
	v_fma_f32 v5, v5, s21, v41
	v_cvt_pk_bf16_f32 v6, v4, v5
	global_store_dword v2, v6, s[18:19]
	s_add_u32 s18, s18, 0x20000
	s_addc_u32 s19, s19, 0
	v_lshlrev_b32_e32 v40, 16, v18
	v_and_b32_e32 v41, 0xffff0000, v18
	v_fma_f32 v4, v4, s21, v40
	v_fma_f32 v5, v5, s21, v41
	v_cvt_pk_bf16_f32 v6, v4, v5
	global_store_dword v2, v6, s[18:19]
	s_add_u32 s18, s18, 0x20000
	s_addc_u32 s19, s19, 0
	v_lshlrev_b32_e32 v40, 16, v19
	v_and_b32_e32 v41, 0xffff0000, v19
	v_fma_f32 v4, v4, s21, v40
	v_fma_f32 v5, v5, s21, v41
	v_cvt_pk_bf16_f32 v6, v4, v5
	global_store_dword v2, v6, s[18:19]
	s_add_u32 s18, s18, 0x20000
	s_addc_u32 s19, s19, 0
	v_lshlrev_b32_e32 v40, 16, v20
	v_and_b32_e32 v41, 0xffff0000, v20
	v_fma_f32 v4, v4, s21, v40
	v_fma_f32 v5, v5, s21, v41
	v_cvt_pk_bf16_f32 v6, v4, v5
	global_store_dword v2, v6, s[18:19]
	s_add_u32 s18, s18, 0x20000
	s_addc_u32 s19, s19, 0
	v_lshlrev_b32_e32 v40, 16, v21
	v_and_b32_e32 v41, 0xffff0000, v21
	v_fma_f32 v4, v4, s21, v40
	v_fma_f32 v5, v5, s21, v41
	v_cvt_pk_bf16_f32 v6, v4, v5
	global_store_dword v2, v6, s[18:19]
	s_add_u32 s18, s18, 0x20000
	s_addc_u32 s19, s19, 0
	v_lshlrev_b32_e32 v40, 16, v22
	v_and_b32_e32 v41, 0xffff0000, v22
	v_fma_f32 v4, v4, s21, v40
	v_fma_f32 v5, v5, s21, v41
	v_cvt_pk_bf16_f32 v6, v4, v5
	global_store_dword v2, v6, s[18:19]
	s_add_u32 s18, s18, 0x20000
	s_addc_u32 s19, s19, 0
	v_lshlrev_b32_e32 v40, 16, v23
	v_and_b32_e32 v41, 0xffff0000, v23
	v_fma_f32 v4, v4, s21, v40
	v_fma_f32 v5, v5, s21, v41
	global_load_dword v16, v2, s[16:17]
	s_add_u32 s16, s16, 0x20000
	s_addc_u32 s17, s17, 0
	global_load_dword v17, v2, s[16:17]
	s_add_u32 s16, s16, 0x20000
	s_addc_u32 s17, s17, 0
	global_load_dword v18, v2, s[16:17]
	s_add_u32 s16, s16, 0x20000
	s_addc_u32 s17, s17, 0
	global_load_dword v19, v2, s[16:17]
	s_add_u32 s16, s16, 0x20000
	s_addc_u32 s17, s17, 0
	global_load_dword v20, v2, s[16:17]
	s_add_u32 s16, s16, 0x20000
	s_addc_u32 s17, s17, 0
	global_load_dword v21, v2, s[16:17]
	s_add_u32 s16, s16, 0x20000
	s_addc_u32 s17, s17, 0
	global_load_dword v22, v2, s[16:17]
	s_add_u32 s16, s16, 0x20000
	s_addc_u32 s17, s17, 0
	global_load_dword v23, v2, s[16:17]
	s_add_u32 s16, s16, 0x20000
	s_addc_u32 s17, s17, 0
	s_waitcnt vmcnt(48)
	v_cvt_pk_bf16_f32 v6, v4, v5
	global_store_dword v2, v6, s[18:19]
	s_add_u32 s18, s18, 0x20000
	s_addc_u32 s19, s19, 0
	v_lshlrev_b32_e32 v40, 16, v24
	v_and_b32_e32 v41, 0xffff0000, v24
	v_fma_f32 v4, v4, s21, v40
	v_fma_f32 v5, v5, s21, v41
	v_cvt_pk_bf16_f32 v6, v4, v5
	global_store_dword v2, v6, s[18:19]
	s_add_u32 s18, s18, 0x20000
	s_addc_u32 s19, s19, 0
	v_lshlrev_b32_e32 v40, 16, v25
	v_and_b32_e32 v41, 0xffff0000, v25
	v_fma_f32 v4, v4, s21, v40
	v_fma_f32 v5, v5, s21, v41
	v_cvt_pk_bf16_f32 v6, v4, v5
	global_store_dword v2, v6, s[18:19]
	s_add_u32 s18, s18, 0x20000
	s_addc_u32 s19, s19, 0
	v_lshlrev_b32_e32 v40, 16, v26
	v_and_b32_e32 v41, 0xffff0000, v26
	v_fma_f32 v4, v4, s21, v40
	v_fma_f32 v5, v5, s21, v41
	v_cvt_pk_bf16_f32 v6, v4, v5
	global_store_dword v2, v6, s[18:19]
	s_add_u32 s18, s18, 0x20000
	s_addc_u32 s19, s19, 0
	v_lshlrev_b32_e32 v40, 16, v27
	v_and_b32_e32 v41, 0xffff0000, v27
	v_fma_f32 v4, v4, s21, v40
	v_fma_f32 v5, v5, s21, v41
	v_cvt_pk_bf16_f32 v6, v4, v5
	global_store_dword v2, v6, s[18:19]
	s_add_u32 s18, s18, 0x20000
	s_addc_u32 s19, s19, 0
	v_lshlrev_b32_e32 v40, 16, v28
	v_and_b32_e32 v41, 0xffff0000, v28
	v_fma_f32 v4, v4, s21, v40
	v_fma_f32 v5, v5, s21, v41
	v_cvt_pk_bf16_f32 v6, v4, v5
	global_store_dword v2, v6, s[18:19]
	s_add_u32 s18, s18, 0x20000
	s_addc_u32 s19, s19, 0
	v_lshlrev_b32_e32 v40, 16, v29
	v_and_b32_e32 v41, 0xffff0000, v29
	v_fma_f32 v4, v4, s21, v40
	v_fma_f32 v5, v5, s21, v41
	v_cvt_pk_bf16_f32 v6, v4, v5
	global_store_dword v2, v6, s[18:19]
	s_add_u32 s18, s18, 0x20000
	s_addc_u32 s19, s19, 0
	v_lshlrev_b32_e32 v40, 16, v30
	v_and_b32_e32 v41, 0xffff0000, v30
	v_fma_f32 v4, v4, s21, v40
	v_fma_f32 v5, v5, s21, v41
	v_cvt_pk_bf16_f32 v6, v4, v5
	global_store_dword v2, v6, s[18:19]
	s_add_u32 s18, s18, 0x20000
	s_addc_u32 s19, s19, 0
	v_lshlrev_b32_e32 v40, 16, v31
	v_and_b32_e32 v41, 0xffff0000, v31
	v_fma_f32 v4, v4, s21, v40
	v_fma_f32 v5, v5, s21, v41
	global_load_dword v24, v2, s[16:17]
	s_add_u32 s16, s16, 0x20000
	s_addc_u32 s17, s17, 0
	global_load_dword v25, v2, s[16:17]
	s_add_u32 s16, s16, 0x20000
	s_addc_u32 s17, s17, 0
	global_load_dword v26, v2, s[16:17]
	s_add_u32 s16, s16, 0x20000
	s_addc_u32 s17, s17, 0
	global_load_dword v27, v2, s[16:17]
	s_add_u32 s16, s16, 0x20000
	s_addc_u32 s17, s17, 0
	global_load_dword v28, v2, s[16:17]
	s_add_u32 s16, s16, 0x20000
	s_addc_u32 s17, s17, 0
	global_load_dword v29, v2, s[16:17]
	s_add_u32 s16, s16, 0x20000
	s_addc_u32 s17, s17, 0
	global_load_dword v30, v2, s[16:17]
	s_add_u32 s16, s16, 0x20000
	s_addc_u32 s17, s17, 0
	global_load_dword v31, v2, s[16:17]
	s_add_u32 s16, s16, 0x20000
	s_addc_u32 s17, s17, 0
	s_waitcnt vmcnt(48)
	v_cvt_pk_bf16_f32 v6, v4, v5
	global_store_dword v2, v6, s[18:19]
	s_add_u32 s18, s18, 0x20000
	s_addc_u32 s19, s19, 0
	v_lshlrev_b32_e32 v40, 16, v32
	v_and_b32_e32 v41, 0xffff0000, v32
	v_fma_f32 v4, v4, s21, v40
	v_fma_f32 v5, v5, s21, v41
	v_cvt_pk_bf16_f32 v6, v4, v5
	global_store_dword v2, v6, s[18:19]
	s_add_u32 s18, s18, 0x20000
	s_addc_u32 s19, s19, 0
	v_lshlrev_b32_e32 v40, 16, v33
	v_and_b32_e32 v41, 0xffff0000, v33
	v_fma_f32 v4, v4, s21, v40
	v_fma_f32 v5, v5, s21, v41
	v_cvt_pk_bf16_f32 v6, v4, v5
	global_store_dword v2, v6, s[18:19]
	s_add_u32 s18, s18, 0x20000
	s_addc_u32 s19, s19, 0
	v_lshlrev_b32_e32 v40, 16, v34
	v_and_b32_e32 v41, 0xffff0000, v34
	v_fma_f32 v4, v4, s21, v40
	v_fma_f32 v5, v5, s21, v41
	v_cvt_pk_bf16_f32 v6, v4, v5
	global_store_dword v2, v6, s[18:19]
	s_add_u32 s18, s18, 0x20000
	s_addc_u32 s19, s19, 0
	v_lshlrev_b32_e32 v40, 16, v35
	v_and_b32_e32 v41, 0xffff0000, v35
	v_fma_f32 v4, v4, s21, v40
	v_fma_f32 v5, v5, s21, v41
	v_cvt_pk_bf16_f32 v6, v4, v5
	global_store_dword v2, v6, s[18:19]
	s_add_u32 s18, s18, 0x20000
	s_addc_u32 s19, s19, 0
	v_lshlrev_b32_e32 v40, 16, v36
	v_and_b32_e32 v41, 0xffff0000, v36
	v_fma_f32 v4, v4, s21, v40
	v_fma_f32 v5, v5, s21, v41
	v_cvt_pk_bf16_f32 v6, v4, v5
	global_store_dword v2, v6, s[18:19]
	s_add_u32 s18, s18, 0x20000
	s_addc_u32 s19, s19, 0
	v_lshlrev_b32_e32 v40, 16, v37
	v_and_b32_e32 v41, 0xffff0000, v37
	v_fma_f32 v4, v4, s21, v40
	v_fma_f32 v5, v5, s21, v41
	v_cvt_pk_bf16_f32 v6, v4, v5
	global_store_dword v2, v6, s[18:19]
	s_add_u32 s18, s18, 0x20000
	s_addc_u32 s19, s19, 0
	v_lshlrev_b32_e32 v40, 16, v38
	v_and_b32_e32 v41, 0xffff0000, v38
	v_fma_f32 v4, v4, s21, v40
	v_fma_f32 v5, v5, s21, v41
	v_cvt_pk_bf16_f32 v6, v4, v5
	global_store_dword v2, v6, s[18:19]
	s_add_u32 s18, s18, 0x20000
	s_addc_u32 s19, s19, 0
	v_lshlrev_b32_e32 v40, 16, v39
	v_and_b32_e32 v41, 0xffff0000, v39
	v_fma_f32 v4, v4, s21, v40
	v_fma_f32 v5, v5, s21, v41
	global_load_dword v32, v2, s[16:17]
	s_add_u32 s16, s16, 0x20000
	s_addc_u32 s17, s17, 0
	global_load_dword v33, v2, s[16:17]
	s_add_u32 s16, s16, 0x20000
	s_addc_u32 s17, s17, 0
	global_load_dword v34, v2, s[16:17]
	s_add_u32 s16, s16, 0x20000
	s_addc_u32 s17, s17, 0
	global_load_dword v35, v2, s[16:17]
	s_add_u32 s16, s16, 0x20000
	s_addc_u32 s17, s17, 0
	global_load_dword v36, v2, s[16:17]
	s_add_u32 s16, s16, 0x20000
	s_addc_u32 s17, s17, 0
	global_load_dword v37, v2, s[16:17]
	s_add_u32 s16, s16, 0x20000
	s_addc_u32 s17, s17, 0
	global_load_dword v38, v2, s[16:17]
	s_add_u32 s16, s16, 0x20000
	s_addc_u32 s17, s17, 0
	global_load_dword v39, v2, s[16:17]
	s_add_u32 s16, s16, 0x20000
	s_addc_u32 s17, s17, 0
	s_sub_u32 s22, s22, 1
	s_cmp_lg_u32 s22, 0
	s_cbranch_scc1 .Lp3_ret_loop
	s_waitcnt vmcnt(48)
	v_cvt_pk_bf16_f32 v6, v4, v5
	global_store_dword v2, v6, s[18:19]
	s_add_u32 s18, s18, 0x20000
	s_addc_u32 s19, s19, 0
	v_lshlrev_b32_e32 v40, 16, v8
	v_and_b32_e32 v41, 0xffff0000, v8
	v_fma_f32 v4, v4, s21, v40
	v_fma_f32 v5, v5, s21, v41
	v_cvt_pk_bf16_f32 v6, v4, v5
	global_store_dword v2, v6, s[18:19]
	s_add_u32 s18, s18, 0x20000
	s_addc_u32 s19, s19, 0
	v_lshlrev_b32_e32 v40, 16, v9
	v_and_b32_e32 v41, 0xffff0000, v9
	v_fma_f32 v4, v4, s21, v40
	v_fma_f32 v5, v5, s21, v41
	v_cvt_pk_bf16_f32 v6, v4, v5
	global_store_dword v2, v6, s[18:19]
	s_add_u32 s18, s18, 0x20000
	s_addc_u32 s19, s19, 0
	v_lshlrev_b32_e32 v40, 16, v10
	v_and_b32_e32 v41, 0xffff0000, v10
	v_fma_f32 v4, v4, s21, v40
	v_fma_f32 v5, v5, s21, v41
	v_cvt_pk_bf16_f32 v6, v4, v5
	global_store_dword v2, v6, s[18:19]
	s_add_u32 s18, s18, 0x20000
	s_addc_u32 s19, s19, 0
	v_lshlrev_b32_e32 v40, 16, v11
	v_and_b32_e32 v41, 0xffff0000, v11
	v_fma_f32 v4, v4, s21, v40
	v_fma_f32 v5, v5, s21, v41
	v_cvt_pk_bf16_f32 v6, v4, v5
	global_store_dword v2, v6, s[18:19]
	s_add_u32 s18, s18, 0x20000
	s_addc_u32 s19, s19, 0
	v_lshlrev_b32_e32 v40, 16, v12
	v_and_b32_e32 v41, 0xffff0000, v12
	v_fma_f32 v4, v4, s21, v40
	v_fma_f32 v5, v5, s21, v41
	v_cvt_pk_bf16_f32 v6, v4, v5
	global_store_dword v2, v6, s[18:19]
	s_add_u32 s18, s18, 0x20000
	s_addc_u32 s19, s19, 0
	v_lshlrev_b32_e32 v40, 16, v13
	v_and_b32_e32 v41, 0xffff0000, v13
	v_fma_f32 v4, v4, s21, v40
	v_fma_f32 v5, v5, s21, v41
	v_cvt_pk_bf16_f32 v6, v4, v5
	global_store_dword v2, v6, s[18:19]
	s_add_u32 s18, s18, 0x20000
	s_addc_u32 s19, s19, 0
	v_lshlrev_b32_e32 v40, 16, v14
	v_and_b32_e32 v41, 0xffff0000, v14
	v_fma_f32 v4, v4, s21, v40
	v_fma_f32 v5, v5, s21, v41
	v_cvt_pk_bf16_f32 v6, v4, v5
	global_store_dword v2, v6, s[18:19]
	s_add_u32 s18, s18, 0x20000
	s_addc_u32 s19, s19, 0
	v_lshlrev_b32_e32 v40, 16, v15
	v_and_b32_e32 v41, 0xffff0000, v15
	v_fma_f32 v4, v4, s21, v40
	v_fma_f32 v5, v5, s21, v41
	s_waitcnt vmcnt(40)
	v_cvt_pk_bf16_f32 v6, v4, v5
	global_store_dword v2, v6, s[18:19]
	s_add_u32 s18, s18, 0x20000
	s_addc_u32 s19, s19, 0
	v_lshlrev_b32_e32 v40, 16, v16
	v_and_b32_e32 v41, 0xffff0000, v16
	v_fma_f32 v4, v4, s21, v40
	v_fma_f32 v5, v5, s21, v41
	v_cvt_pk_bf16_f32 v6, v4, v5
	global_store_dword v2, v6, s[18:19]
	s_add_u32 s18, s18, 0x20000
	s_addc_u32 s19, s19, 0
	v_lshlrev_b32_e32 v40, 16, v17
	v_and_b32_e32 v41, 0xffff0000, v17
	v_fma_f32 v4, v4, s21, v40
	v_fma_f32 v5, v5, s21, v41
	v_cvt_pk_bf16_f32 v6, v4, v5
	global_store_dword v2, v6, s[18:19]
	s_add_u32 s18, s18, 0x20000
	s_addc_u32 s19, s19, 0
	v_lshlrev_b32_e32 v40, 16, v18
	v_and_b32_e32 v41, 0xffff0000, v18
	v_fma_f32 v4, v4, s21, v40
	v_fma_f32 v5, v5, s21, v41
	v_cvt_pk_bf16_f32 v6, v4, v5
	global_store_dword v2, v6, s[18:19]
	s_add_u32 s18, s18, 0x20000
	s_addc_u32 s19, s19, 0
	v_lshlrev_b32_e32 v40, 16, v19
	v_and_b32_e32 v41, 0xffff0000, v19
	v_fma_f32 v4, v4, s21, v40
	v_fma_f32 v5, v5, s21, v41
	v_cvt_pk_bf16_f32 v6, v4, v5
	global_store_dword v2, v6, s[18:19]
	s_add_u32 s18, s18, 0x20000
	s_addc_u32 s19, s19, 0
	v_lshlrev_b32_e32 v40, 16, v20
	v_and_b32_e32 v41, 0xffff0000, v20
	v_fma_f32 v4, v4, s21, v40
	v_fma_f32 v5, v5, s21, v41
	v_cvt_pk_bf16_f32 v6, v4, v5
	global_store_dword v2, v6, s[18:19]
	s_add_u32 s18, s18, 0x20000
	s_addc_u32 s19, s19, 0
	v_lshlrev_b32_e32 v40, 16, v21
	v_and_b32_e32 v41, 0xffff0000, v21
	v_fma_f32 v4, v4, s21, v40
	v_fma_f32 v5, v5, s21, v41
	v_cvt_pk_bf16_f32 v6, v4, v5
	global_store_dword v2, v6, s[18:19]
	s_add_u32 s18, s18, 0x20000
	s_addc_u32 s19, s19, 0
	v_lshlrev_b32_e32 v40, 16, v22
	v_and_b32_e32 v41, 0xffff0000, v22
	v_fma_f32 v4, v4, s21, v40
	v_fma_f32 v5, v5, s21, v41
	v_cvt_pk_bf16_f32 v6, v4, v5
	global_store_dword v2, v6, s[18:19]
	s_add_u32 s18, s18, 0x20000
	s_addc_u32 s19, s19, 0
	v_lshlrev_b32_e32 v40, 16, v23
	v_and_b32_e32 v41, 0xffff0000, v23
	v_fma_f32 v4, v4, s21, v40
	v_fma_f32 v5, v5, s21, v41
	s_waitcnt vmcnt(32)
	v_cvt_pk_bf16_f32 v6, v4, v5
	global_store_dword v2, v6, s[18:19]
	s_add_u32 s18, s18, 0x20000
	s_addc_u32 s19, s19, 0
	v_lshlrev_b32_e32 v40, 16, v24
	v_and_b32_e32 v41, 0xffff0000, v24
	v_fma_f32 v4, v4, s21, v40
	v_fma_f32 v5, v5, s21, v41
	v_cvt_pk_bf16_f32 v6, v4, v5
	global_store_dword v2, v6, s[18:19]
	s_add_u32 s18, s18, 0x20000
	s_addc_u32 s19, s19, 0
	v_lshlrev_b32_e32 v40, 16, v25
	v_and_b32_e32 v41, 0xffff0000, v25
	v_fma_f32 v4, v4, s21, v40
	v_fma_f32 v5, v5, s21, v41
	v_cvt_pk_bf16_f32 v6, v4, v5
	global_store_dword v2, v6, s[18:19]
	s_add_u32 s18, s18, 0x20000
	s_addc_u32 s19, s19, 0
	v_lshlrev_b32_e32 v40, 16, v26
	v_and_b32_e32 v41, 0xffff0000, v26
	v_fma_f32 v4, v4, s21, v40
	v_fma_f32 v5, v5, s21, v41
	v_cvt_pk_bf16_f32 v6, v4, v5
	global_store_dword v2, v6, s[18:19]
	s_add_u32 s18, s18, 0x20000
	s_addc_u32 s19, s19, 0
	v_lshlrev_b32_e32 v40, 16, v27
	v_and_b32_e32 v41, 0xffff0000, v27
	v_fma_f32 v4, v4, s21, v40
	v_fma_f32 v5, v5, s21, v41
	v_cvt_pk_bf16_f32 v6, v4, v5
	global_store_dword v2, v6, s[18:19]
	s_add_u32 s18, s18, 0x20000
	s_addc_u32 s19, s19, 0
	v_lshlrev_b32_e32 v40, 16, v28
	v_and_b32_e32 v41, 0xffff0000, v28
	v_fma_f32 v4, v4, s21, v40
	v_fma_f32 v5, v5, s21, v41
	v_cvt_pk_bf16_f32 v6, v4, v5
	global_store_dword v2, v6, s[18:19]
	s_add_u32 s18, s18, 0x20000
	s_addc_u32 s19, s19, 0
	v_lshlrev_b32_e32 v40, 16, v29
	v_and_b32_e32 v41, 0xffff0000, v29
	v_fma_f32 v4, v4, s21, v40
	v_fma_f32 v5, v5, s21, v41
	v_cvt_pk_bf16_f32 v6, v4, v5
	global_store_dword v2, v6, s[18:19]
	s_add_u32 s18, s18, 0x20000
	s_addc_u32 s19, s19, 0
	v_lshlrev_b32_e32 v40, 16, v30
	v_and_b32_e32 v41, 0xffff0000, v30
	v_fma_f32 v4, v4, s21, v40
	v_fma_f32 v5, v5, s21, v41
	v_cvt_pk_bf16_f32 v6, v4, v5
	global_store_dword v2, v6, s[18:19]
	s_add_u32 s18, s18, 0x20000
	s_addc_u32 s19, s19, 0
	v_lshlrev_b32_e32 v40, 16, v31
	v_and_b32_e32 v41, 0xffff0000, v31
	v_fma_f32 v4, v4, s21, v40
	v_fma_f32 v5, v5, s21, v41
	s_waitcnt vmcnt(24)
	v_cvt_pk_bf16_f32 v6, v4, v5
	global_store_dword v2, v6, s[18:19]
	s_add_u32 s18, s18, 0x20000
	s_addc_u32 s19, s19, 0
	v_lshlrev_b32_e32 v40, 16, v32
	v_and_b32_e32 v41, 0xffff0000, v32
	v_fma_f32 v4, v4, s21, v40
	v_fma_f32 v5, v5, s21, v41
	v_cvt_pk_bf16_f32 v6, v4, v5
	global_store_dword v2, v6, s[18:19]
	s_add_u32 s18, s18, 0x20000
	s_addc_u32 s19, s19, 0
	v_lshlrev_b32_e32 v40, 16, v33
	v_and_b32_e32 v41, 0xffff0000, v33
	v_fma_f32 v4, v4, s21, v40
	v_fma_f32 v5, v5, s21, v41
	v_cvt_pk_bf16_f32 v6, v4, v5
	global_store_dword v2, v6, s[18:19]
	s_add_u32 s18, s18, 0x20000
	s_addc_u32 s19, s19, 0
	v_lshlrev_b32_e32 v40, 16, v34
	v_and_b32_e32 v41, 0xffff0000, v34
	v_fma_f32 v4, v4, s21, v40
	v_fma_f32 v5, v5, s21, v41
	v_cvt_pk_bf16_f32 v6, v4, v5
	global_store_dword v2, v6, s[18:19]
	s_add_u32 s18, s18, 0x20000
	s_addc_u32 s19, s19, 0
	v_lshlrev_b32_e32 v40, 16, v35
	v_and_b32_e32 v41, 0xffff0000, v35
	v_fma_f32 v4, v4, s21, v40
	v_fma_f32 v5, v5, s21, v41
	v_cvt_pk_bf16_f32 v6, v4, v5
	global_store_dword v2, v6, s[18:19]
	s_add_u32 s18, s18, 0x20000
	s_addc_u32 s19, s19, 0
	v_lshlrev_b32_e32 v40, 16, v36
	v_and_b32_e32 v41, 0xffff0000, v36
	v_fma_f32 v4, v4, s21, v40
	v_fma_f32 v5, v5, s21, v41
	v_cvt_pk_bf16_f32 v6, v4, v5
	global_store_dword v2, v6, s[18:19]
	s_add_u32 s18, s18, 0x20000
	s_addc_u32 s19, s19, 0
	v_lshlrev_b32_e32 v40, 16, v37
	v_and_b32_e32 v41, 0xffff0000, v37
	v_fma_f32 v4, v4, s21, v40
	v_fma_f32 v5, v5, s21, v41
	v_cvt_pk_bf16_f32 v6, v4, v5
	global_store_dword v2, v6, s[18:19]
	s_add_u32 s18, s18, 0x20000
	s_addc_u32 s19, s19, 0
	v_lshlrev_b32_e32 v40, 16, v38
	v_and_b32_e32 v41, 0xffff0000, v38
	v_fma_f32 v4, v4, s21, v40
	v_fma_f32 v5, v5, s21, v41
	v_cvt_pk_bf16_f32 v6, v4, v5
	global_store_dword v2, v6, s[18:19]
	s_add_u32 s18, s18, 0x20000
	s_addc_u32 s19, s19, 0
	v_lshlrev_b32_e32 v40, 16, v39
	v_and_b32_e32 v41, 0xffff0000, v39
	v_fma_f32 v4, v4, s21, v40
	v_fma_f32 v5, v5, s21, v41
	s_branch .Lp3_done
.Lp3_ssd:
	s_add_u32 s16, s8, s15
	s_addc_u32 s17, s9, 0
	s_add_u32 s16, s16, 0x4000000
	s_addc_u32 s17, s17, 0
	s_mov_b64 s[18:19], s[16:17]
	v_add_u32_e32 v1, 0xffff8000, v1
	v_lshlrev_b32_e32 v2, 2, v1
	s_sub_u32 s20, s14, 0x8000
	s_lshr_b32 s20, s20, 12
	s_lshl_b32 s23, s13, 11
	s_add_u32 s20, s20, s23
	s_lshl_b32 s20, s20, 2
	s_add_u32 s24, s10, 0x3f2a000
	s_addc_u32 s25, s11, 0
	s_add_u32 s24, s24, s20
	s_addc_u32 s25, s25, 0
	v_mov_b32_e32 v4, 0
	v_mov_b32_e32 v5, 0
	global_load_dword v8, v2, s[16:17]
	s_add_u32 s16, s16, 0x20000
	s_addc_u32 s17, s17, 0
	global_load_dword v9, v2, s[16:17]
	s_add_u32 s16, s16, 0x20000
	s_addc_u32 s17, s17, 0
	global_load_dword v10, v2, s[16:17]
	s_add_u32 s16, s16, 0x20000
	s_addc_u32 s17, s17, 0
	global_load_dword v11, v2, s[16:17]
	s_add_u32 s16, s16, 0x20000
	s_addc_u32 s17, s17, 0
	global_load_dword v12, v2, s[16:17]
	s_add_u32 s16, s16, 0x20000
	s_addc_u32 s17, s17, 0
	global_load_dword v13, v2, s[16:17]
	s_add_u32 s16, s16, 0x20000
	s_addc_u32 s17, s17, 0
	global_load_dword v14, v2, s[16:17]
	s_add_u32 s16, s16, 0x20000
	s_addc_u32 s17, s17, 0
	global_load_dword v15, v2, s[16:17]
	s_add_u32 s16, s16, 0x20000
	s_addc_u32 s17, s17, 0
	s_load_dword s32, s[24:25], 0x0
	s_load_dword s33, s[24:25], 0x20
	s_load_dword s34, s[24:25], 0x40
	s_load_dword s35, s[24:25], 0x60
	s_load_dword s36, s[24:25], 0x80
	s_load_dword s37, s[24:25], 0xa0
	s_load_dword s38, s[24:25], 0xc0
	s_load_dword s39, s[24:25], 0xe0
	s_add_u32 s24, s24, 0x100
	s_addc_u32 s25, s25, 0
	global_load_dword v16, v2, s[16:17]
	s_add_u32 s16, s16, 0x20000
	s_addc_u32 s17, s17, 0
	global_load_dword v17, v2, s[16:17]
	s_add_u32 s16, s16, 0x20000
	s_addc_u32 s17, s17, 0
	global_load_dword v18, v2, s[16:17]
	s_add_u32 s16, s16, 0x20000
	s_addc_u32 s17, s17, 0
	global_load_dword v19, v2, s[16:17]
	s_add_u32 s16, s16, 0x20000
	s_addc_u32 s17, s17, 0
	global_load_dword v20, v2, s[16:17]
	s_add_u32 s16, s16, 0x20000
	s_addc_u32 s17, s17, 0
	global_load_dword v21, v2, s[16:17]
	s_add_u32 s16, s16, 0x20000
	s_addc_u32 s17, s17, 0
	global_load_dword v22, v2, s[16:17]
	s_add_u32 s16, s16, 0x20000
	s_addc_u32 s17, s17, 0
	global_load_dword v23, v2, s[16:17]
	s_add_u32 s16, s16, 0x20000
	s_addc_u32 s17, s17, 0
	s_load_dword s40, s[24:25], 0x0
	s_load_dword s41, s[24:25], 0x20
	s_load_dword s42, s[24:25], 0x40
	s_load_dword s43, s[24:25], 0x60
	s_load_dword s44, s[24:25], 0x80
	s_load_dword s45, s[24:25], 0xa0
	s_load_dword s46, s[24:25], 0xc0
	s_load_dword s47, s[24:25], 0xe0
	s_add_u32 s24, s24, 0x100
	s_addc_u32 s25, s25, 0
	global_load_dword v24, v2, s[16:17]
	s_add_u32 s16, s16, 0x20000
	s_addc_u32 s17, s17, 0
	global_load_dword v25, v2, s[16:17]
	s_add_u32 s16, s16, 0x20000
	s_addc_u32 s17, s17, 0
	global_load_dword v26, v2, s[16:17]
	s_add_u32 s16, s16, 0x20000
	s_addc_u32 s17, s17, 0
	global_load_dword v27, v2, s[16:17]
	s_add_u32 s16, s16, 0x20000
	s_addc_u32 s17, s17, 0
	global_load_dword v28, v2, s[16:17]
	s_add_u32 s16, s16, 0x20000
	s_addc_u32 s17, s17, 0
	global_load_dword v29, v2, s[16:17]
	s_add_u32 s16, s16, 0x20000
	s_addc_u32 s17, s17, 0
	global_load_dword v30, v2, s[16:17]
	s_add_u32 s16, s16, 0x20000
	s_addc_u32 s17, s17, 0
	global_load_dword v31, v2, s[16:17]
	s_add_u32 s16, s16, 0x20000
	s_addc_u32 s17, s17, 0
	s_load_dword s48, s[24:25], 0x0
	s_load_dword s49, s[24:25], 0x20
	s_load_dword s50, s[24:25], 0x40
	s_load_dword s51, s[24:25], 0x60
	s_load_dword s52, s[24:25], 0x80
	s_load_dword s53, s[24:25], 0xa0
	s_load_dword s54, s[24:25], 0xc0
	s_load_dword s55, s[24:25], 0xe0
	s_add_u32 s24, s24, 0x100
	s_addc_u32 s25, s25, 0
	global_load_dword v32, v2, s[16:17]
	s_add_u32 s16, s16, 0x20000
	s_addc_u32 s17, s17, 0
	global_load_dword v33, v2, s[16:17]
	s_add_u32 s16, s16, 0x20000
	s_addc_u32 s17, s17, 0
	global_load_dword v34, v2, s[16:17]
	s_add_u32 s16, s16, 0x20000
	s_addc_u32 s17, s17, 0
	global_load_dword v35, v2, s[16:17]
	s_add_u32 s16, s16, 0x20000
	s_addc_u32 s17, s17, 0
	global_load_dword v36, v2, s[16:17]
	s_add_u32 s16, s16, 0x20000
	s_addc_u32 s17, s17, 0
	global_load_dword v37, v2, s[16:17]
	s_add_u32 s16, s16, 0x20000
	s_addc_u32 s17, s17, 0
	global_load_dword v38, v2, s[16:17]
	s_add_u32 s16, s16, 0x20000
	s_addc_u32 s17, s17, 0
	global_load_dword v39, v2, s[16:17]
	s_add_u32 s16, s16, 0x20000
	s_addc_u32 s17, s17, 0
	s_load_dword s56, s[24:25], 0x0
	s_load_dword s57, s[24:25], 0x20
	s_load_dword s58, s[24:25], 0x40
	s_load_dword s59, s[24:25], 0x60
	s_load_dword s60, s[24:25], 0x80
	s_load_dword s61, s[24:25], 0xa0
	s_load_dword s62, s[24:25], 0xc0
	s_load_dword s63, s[24:25], 0xe0
	s_add_u32 s24, s24, 0x100
	s_addc_u32 s25, s25, 0
	s_waitcnt vmcnt(24) lgkmcnt(0)
	v_cvt_pk_bf16_f32 v6, v4, v5
	global_store_dword v2, v6, s[18:19]
	s_add_u32 s18, s18, 0x20000
	s_addc_u32 s19, s19, 0
	v_lshlrev_b32_e32 v40, 16, v8
	v_and_b32_e32 v41, 0xffff0000, v8
	v_fma_f32 v4, v4, s32, v40
	v_fma_f32 v5, v5, s32, v41
	v_cvt_pk_bf16_f32 v6, v4, v5
	global_store_dword v2, v6, s[18:19]
	s_add_u32 s18, s18, 0x20000
	s_addc_u32 s19, s19, 0
	v_lshlrev_b32_e32 v40, 16, v9
	v_and_b32_e32 v41, 0xffff0000, v9
	v_fma_f32 v4, v4, s33, v40
	v_fma_f32 v5, v5, s33, v41
	v_cvt_pk_bf16_f32 v6, v4, v5
	global_store_dword v2, v6, s[18:19]
	s_add_u32 s18, s18, 0x20000
	s_addc_u32 s19, s19, 0
	v_lshlrev_b32_e32 v40, 16, v10
	v_and_b32_e32 v41, 0xffff0000, v10
	v_fma_f32 v4, v4, s34, v40
	v_fma_f32 v5, v5, s34, v41
	v_cvt_pk_bf16_f32 v6, v4, v5
	global_store_dword v2, v6, s[18:19]
	s_add_u32 s18, s18, 0x20000
	s_addc_u32 s19, s19, 0
	v_lshlrev_b32_e32 v40, 16, v11
	v_and_b32_e32 v41, 0xffff0000, v11
	v_fma_f32 v4, v4, s35, v40
	v_fma_f32 v5, v5, s35, v41
	v_cvt_pk_bf16_f32 v6, v4, v5
	global_store_dword v2, v6, s[18:19]
	s_add_u32 s18, s18, 0x20000
	s_addc_u32 s19, s19, 0
	v_lshlrev_b32_e32 v40, 16, v12
	v_and_b32_e32 v41, 0xffff0000, v12
	v_fma_f32 v4, v4, s36, v40
	v_fma_f32 v5, v5, s36, v41
	v_cvt_pk_bf16_f32 v6, v4, v5
	global_store_dword v2, v6, s[18:19]
	s_add_u32 s18, s18, 0x20000
	s_addc_u32 s19, s19, 0
	v_lshlrev_b32_e32 v40, 16, v13
	v_and_b32_e32 v41, 0xffff0000, v13
	v_fma_f32 v4, v4, s37, v40
	v_fma_f32 v5, v5, s37, v41
	v_cvt_pk_bf16_f32 v6, v4, v5
	global_store_dword v2, v6, s[18:19]
	s_add_u32 s18, s18, 0x20000
	s_addc_u32 s19, s19, 0
	v_lshlrev_b32_e32 v40, 16, v14
	v_and_b32_e32 v41, 0xffff0000, v14
	v_fma_f32 v4, v4, s38, v40
	v_fma_f32 v5, v5, s38, v41
	v_cvt_pk_bf16_f32 v6, v4, v5
	global_store_dword v2, v6, s[18:19]
	s_add_u32 s18, s18, 0x20000
	s_addc_u32 s19, s19, 0
	v_lshlrev_b32_e32 v40, 16, v15
	v_and_b32_e32 v41, 0xffff0000, v15
	v_fma_f32 v4, v4, s39, v40
	v_fma_f32 v5, v5, s39, v41
	global_load_dword v8, v2, s[16:17]
	s_add_u32 s16, s16, 0x20000
	s_addc_u32 s17, s17, 0
	global_load_dword v9, v2, s[16:17]
	s_add_u32 s16, s16, 0x20000
	s_addc_u32 s17, s17, 0
	global_load_dword v10, v2, s[16:17]
	s_add_u32 s16, s16, 0x20000
	s_addc_u32 s17, s17, 0
	global_load_dword v11, v2, s[16:17]
	s_add_u32 s16, s16, 0x20000
	s_addc_u32 s17, s17, 0
	global_load_dword v12, v2, s[16:17]
	s_add_u32 s16, s16, 0x20000
	s_addc_u32 s17, s17, 0
	global_load_dword v13, v2, s[16:17]
	s_add_u32 s16, s16, 0x20000
	s_addc_u32 s17, s17, 0
	global_load_dword v14, v2, s[16:17]
	s_add_u32 s16, s16, 0x20000
	s_addc_u32 s17, s17, 0
	global_load_dword v15, v2, s[16:17]
	s_add_u32 s16, s16, 0x20000
	s_addc_u32 s17, s17, 0
	s_load_dword s32, s[24:25], 0x0
	s_load_dword s33, s[24:25], 0x20
	s_load_dword s34, s[24:25], 0x40
	s_load_dword s35, s[24:25], 0x60
	s_load_dword s36, s[24:25], 0x80
	s_load_dword s37, s[24:25], 0xa0
	s_load_dword s38, s[24:25], 0xc0
	s_load_dword s39, s[24:25], 0xe0
	s_add_u32 s24, s24, 0x100
	s_addc_u32 s25, s25, 0
	s_waitcnt vmcnt(32) lgkmcnt(0)
	v_cvt_pk_bf16_f32 v6, v4, v5
	global_store_dword v2, v6, s[18:19]
	s_add_u32 s18, s18, 0x20000
	s_addc_u32 s19, s19, 0
	v_lshlrev_b32_e32 v40, 16, v16
	v_and_b32_e32 v41, 0xffff0000, v16
	v_fma_f32 v4, v4, s40, v40
	v_fma_f32 v5, v5, s40, v41
	v_cvt_pk_bf16_f32 v6, v4, v5
	global_store_dword v2, v6, s[18:19]
	s_add_u32 s18, s18, 0x20000
	s_addc_u32 s19, s19, 0
	v_lshlrev_b32_e32 v40, 16, v17
	v_and_b32_e32 v41, 0xffff0000, v17
	v_fma_f32 v4, v4, s41, v40
	v_fma_f32 v5, v5, s41, v41
	v_cvt_pk_bf16_f32 v6, v4, v5
	global_store_dword v2, v6, s[18:19]
	s_add_u32 s18, s18, 0x20000
	s_addc_u32 s19, s19, 0
	v_lshlrev_b32_e32 v40, 16, v18
	v_and_b32_e32 v41, 0xffff0000, v18
	v_fma_f32 v4, v4, s42, v40
	v_fma_f32 v5, v5, s42, v41
	v_cvt_pk_bf16_f32 v6, v4, v5
	global_store_dword v2, v6, s[18:19]
	s_add_u32 s18, s18, 0x20000
	s_addc_u32 s19, s19, 0
	v_lshlrev_b32_e32 v40, 16, v19
	v_and_b32_e32 v41, 0xffff0000, v19
	v_fma_f32 v4, v4, s43, v40
	v_fma_f32 v5, v5, s43, v41
	v_cvt_pk_bf16_f32 v6, v4, v5
	global_store_dword v2, v6, s[18:19]
	s_add_u32 s18, s18, 0x20000
	s_addc_u32 s19, s19, 0
	v_lshlrev_b32_e32 v40, 16, v20
	v_and_b32_e32 v41, 0xffff0000, v20
	v_fma_f32 v4, v4, s44, v40
	v_fma_f32 v5, v5, s44, v41
	v_cvt_pk_bf16_f32 v6, v4, v5
	global_store_dword v2, v6, s[18:19]
	s_add_u32 s18, s18, 0x20000
	s_addc_u32 s19, s19, 0
	v_lshlrev_b32_e32 v40, 16, v21
	v_and_b32_e32 v41, 0xffff0000, v21
	v_fma_f32 v4, v4, s45, v40
	v_fma_f32 v5, v5, s45, v41
	v_cvt_pk_bf16_f32 v6, v4, v5
	global_store_dword v2, v6, s[18:19]
	s_add_u32 s18, s18, 0x20000
	s_addc_u32 s19, s19, 0
	v_lshlrev_b32_e32 v40, 16, v22
	v_and_b32_e32 v41, 0xffff0000, v22
	v_fma_f32 v4, v4, s46, v40
	v_fma_f32 v5, v5, s46, v41
	v_cvt_pk_bf16_f32 v6, v4, v5
	global_store_dword v2, v6, s[18:19]
	s_add_u32 s18, s18, 0x20000
	s_addc_u32 s19, s19, 0
	v_lshlrev_b32_e32 v40, 16, v23
	v_and_b32_e32 v41, 0xffff0000, v23
	v_fma_f32 v4, v4, s47, v40
	v_fma_f32 v5, v5, s47, v41
	global_load_dword v16, v2, s[16:17]
	s_add_u32 s16, s16, 0x20000
	s_addc_u32 s17, s17, 0
	global_load_dword v17, v2, s[16:17]
	s_add_u32 s16, s16, 0x20000
	s_addc_u32 s17, s17, 0
	global_load_dword v18, v2, s[16:17]
	s_add_u32 s16, s16, 0x20000
	s_addc_u32 s17, s17, 0
	global_load_dword v19, v2, s[16:17]
	s_add_u32 s16, s16, 0x20000
	s_addc_u32 s17, s17, 0
	global_load_dword v20, v2, s[16:17]
	s_add_u32 s16, s16, 0x20000
	s_addc_u32 s17, s17, 0
	global_load_dword v21, v2, s[16:17]
	s_add_u32 s16, s16, 0x20000
	s_addc_u32 s17, s17, 0
	global_load_dword v22, v2, s[16:17]
	s_add_u32 s16, s16, 0x20000
	s_addc_u32 s17, s17, 0
	global_load_dword v23, v2, s[16:17]
	s_add_u32 s16, s16, 0x20000
	s_addc_u32 s17, s17, 0
	s_load_dword s40, s[24:25], 0x0
	s_load_dword s41, s[24:25], 0x20
	s_load_dword s42, s[24:25], 0x40
	s_load_dword s43, s[24:25], 0x60
	s_load_dword s44, s[24:25], 0x80
	s_load_dword s45, s[24:25], 0xa0
	s_load_dword s46, s[24:25], 0xc0
	s_load_dword s47, s[24:25], 0xe0
	s_add_u32 s24, s24, 0x100
	s_addc_u32 s25, s25, 0
	s_waitcnt vmcnt(40) lgkmcnt(0)
	v_cvt_pk_bf16_f32 v6, v4, v5
	global_store_dword v2, v6, s[18:19]
	s_add_u32 s18, s18, 0x20000
	s_addc_u32 s19, s19, 0
	v_lshlrev_b32_e32 v40, 16, v24
	v_and_b32_e32 v41, 0xffff0000, v24
	v_fma_f32 v4, v4, s48, v40
	v_fma_f32 v5, v5, s48, v41
	v_cvt_pk_bf16_f32 v6, v4, v5
	global_store_dword v2, v6, s[18:19]
	s_add_u32 s18, s18, 0x20000
	s_addc_u32 s19, s19, 0
	v_lshlrev_b32_e32 v40, 16, v25
	v_and_b32_e32 v41, 0xffff0000, v25
	v_fma_f32 v4, v4, s49, v40
	v_fma_f32 v5, v5, s49, v41
	v_cvt_pk_bf16_f32 v6, v4, v5
	global_store_dword v2, v6, s[18:19]
	s_add_u32 s18, s18, 0x20000
	s_addc_u32 s19, s19, 0
	v_lshlrev_b32_e32 v40, 16, v26
	v_and_b32_e32 v41, 0xffff0000, v26
	v_fma_f32 v4, v4, s50, v40
	v_fma_f32 v5, v5, s50, v41
	v_cvt_pk_bf16_f32 v6, v4, v5
	global_store_dword v2, v6, s[18:19]
	s_add_u32 s18, s18, 0x20000
	s_addc_u32 s19, s19, 0
	v_lshlrev_b32_e32 v40, 16, v27
	v_and_b32_e32 v41, 0xffff0000, v27
	v_fma_f32 v4, v4, s51, v40
	v_fma_f32 v5, v5, s51, v41
	v_cvt_pk_bf16_f32 v6, v4, v5
	global_store_dword v2, v6, s[18:19]
	s_add_u32 s18, s18, 0x20000
	s_addc_u32 s19, s19, 0
	v_lshlrev_b32_e32 v40, 16, v28
	v_and_b32_e32 v41, 0xffff0000, v28
	v_fma_f32 v4, v4, s52, v40
	v_fma_f32 v5, v5, s52, v41
	v_cvt_pk_bf16_f32 v6, v4, v5
	global_store_dword v2, v6, s[18:19]
	s_add_u32 s18, s18, 0x20000
	s_addc_u32 s19, s19, 0
	v_lshlrev_b32_e32 v40, 16, v29
	v_and_b32_e32 v41, 0xffff0000, v29
	v_fma_f32 v4, v4, s53, v40
	v_fma_f32 v5, v5, s53, v41
	v_cvt_pk_bf16_f32 v6, v4, v5
	global_store_dword v2, v6, s[18:19]
	s_add_u32 s18, s18, 0x20000
	s_addc_u32 s19, s19, 0
	v_lshlrev_b32_e32 v40, 16, v30
	v_and_b32_e32 v41, 0xffff0000, v30
	v_fma_f32 v4, v4, s54, v40
	v_fma_f32 v5, v5, s54, v41
	v_cvt_pk_bf16_f32 v6, v4, v5
	global_store_dword v2, v6, s[18:19]
	s_add_u32 s18, s18, 0x20000
	s_addc_u32 s19, s19, 0
	v_lshlrev_b32_e32 v40, 16, v31
	v_and_b32_e32 v41, 0xffff0000, v31
	v_fma_f32 v4, v4, s55, v40
	v_fma_f32 v5, v5, s55, v41
	global_load_dword v24, v2, s[16:17]
	s_add_u32 s16, s16, 0x20000
	s_addc_u32 s17, s17, 0
	global_load_dword v25, v2, s[16:17]
	s_add_u32 s16, s16, 0x20000
	s_addc_u32 s17, s17, 0
	global_load_dword v26, v2, s[16:17]
	s_add_u32 s16, s16, 0x20000
	s_addc_u32 s17, s17, 0
	global_load_dword v27, v2, s[16:17]
	s_add_u32 s16, s16, 0x20000
	s_addc_u32 s17, s17, 0
	global_load_dword v28, v2, s[16:17]
	s_add_u32 s16, s16, 0x20000
	s_addc_u32 s17, s17, 0
	global_load_dword v29, v2, s[16:17]
	s_add_u32 s16, s16, 0x20000
	s_addc_u32 s17, s17, 0
	global_load_dword v30, v2, s[16:17]
	s_add_u32 s16, s16, 0x20000
	s_addc_u32 s17, s17, 0
	global_load_dword v31, v2, s[16:17]
	s_add_u32 s16, s16, 0x20000
	s_addc_u32 s17, s17, 0
	s_load_dword s48, s[24:25], 0x0
	s_load_dword s49, s[24:25], 0x20
	s_load_dword s50, s[24:25], 0x40
	s_load_dword s51, s[24:25], 0x60
	s_load_dword s52, s[24:25], 0x80
	s_load_dword s53, s[24:25], 0xa0
	s_load_dword s54, s[24:25], 0xc0
	s_load_dword s55, s[24:25], 0xe0
	s_add_u32 s24, s24, 0x100
	s_addc_u32 s25, s25, 0
	s_waitcnt vmcnt(48) lgkmcnt(0)
	v_cvt_pk_bf16_f32 v6, v4, v5
	global_store_dword v2, v6, s[18:19]
	s_add_u32 s18, s18, 0x20000
	s_addc_u32 s19, s19, 0
	v_lshlrev_b32_e32 v40, 16, v32
	v_and_b32_e32 v41, 0xffff0000, v32
	v_fma_f32 v4, v4, s56, v40
	v_fma_f32 v5, v5, s56, v41
	v_cvt_pk_bf16_f32 v6, v4, v5
	global_store_dword v2, v6, s[18:19]
	s_add_u32 s18, s18, 0x20000
	s_addc_u32 s19, s19, 0
	v_lshlrev_b32_e32 v40, 16, v33
	v_and_b32_e32 v41, 0xffff0000, v33
	v_fma_f32 v4, v4, s57, v40
	v_fma_f32 v5, v5, s57, v41
	v_cvt_pk_bf16_f32 v6, v4, v5
	global_store_dword v2, v6, s[18:19]
	s_add_u32 s18, s18, 0x20000
	s_addc_u32 s19, s19, 0
	v_lshlrev_b32_e32 v40, 16, v34
	v_and_b32_e32 v41, 0xffff0000, v34
	v_fma_f32 v4, v4, s58, v40
	v_fma_f32 v5, v5, s58, v41
	v_cvt_pk_bf16_f32 v6, v4, v5
	global_store_dword v2, v6, s[18:19]
	s_add_u32 s18, s18, 0x20000
	s_addc_u32 s19, s19, 0
	v_lshlrev_b32_e32 v40, 16, v35
	v_and_b32_e32 v41, 0xffff0000, v35
	v_fma_f32 v4, v4, s59, v40
	v_fma_f32 v5, v5, s59, v41
	v_cvt_pk_bf16_f32 v6, v4, v5
	global_store_dword v2, v6, s[18:19]
	s_add_u32 s18, s18, 0x20000
	s_addc_u32 s19, s19, 0
	v_lshlrev_b32_e32 v40, 16, v36
	v_and_b32_e32 v41, 0xffff0000, v36
	v_fma_f32 v4, v4, s60, v40
	v_fma_f32 v5, v5, s60, v41
	v_cvt_pk_bf16_f32 v6, v4, v5
	global_store_dword v2, v6, s[18:19]
	s_add_u32 s18, s18, 0x20000
	s_addc_u32 s19, s19, 0
	v_lshlrev_b32_e32 v40, 16, v37
	v_and_b32_e32 v41, 0xffff0000, v37
	v_fma_f32 v4, v4, s61, v40
	v_fma_f32 v5, v5, s61, v41
	v_cvt_pk_bf16_f32 v6, v4, v5
	global_store_dword v2, v6, s[18:19]
	s_add_u32 s18, s18, 0x20000
	s_addc_u32 s19, s19, 0
	v_lshlrev_b32_e32 v40, 16, v38
	v_and_b32_e32 v41, 0xffff0000, v38
	v_fma_f32 v4, v4, s62, v40
	v_fma_f32 v5, v5, s62, v41
	v_cvt_pk_bf16_f32 v6, v4, v5
	global_store_dword v2, v6, s[18:19]
	s_add_u32 s18, s18, 0x20000
	s_addc_u32 s19, s19, 0
	v_lshlrev_b32_e32 v40, 16, v39
	v_and_b32_e32 v41, 0xffff0000, v39
	v_fma_f32 v4, v4, s63, v40
	v_fma_f32 v5, v5, s63, v41
	global_load_dword v32, v2, s[16:17]
	s_add_u32 s16, s16, 0x20000
	s_addc_u32 s17, s17, 0
	global_load_dword v33, v2, s[16:17]
	s_add_u32 s16, s16, 0x20000
	s_addc_u32 s17, s17, 0
	global_load_dword v34, v2, s[16:17]
	s_add_u32 s16, s16, 0x20000
	s_addc_u32 s17, s17, 0
	global_load_dword v35, v2, s[16:17]
	s_add_u32 s16, s16, 0x20000
	s_addc_u32 s17, s17, 0
	global_load_dword v36, v2, s[16:17]
	s_add_u32 s16, s16, 0x20000
	s_addc_u32 s17, s17, 0
	global_load_dword v37, v2, s[16:17]
	s_add_u32 s16, s16, 0x20000
	s_addc_u32 s17, s17, 0
	global_load_dword v38, v2, s[16:17]
	s_add_u32 s16, s16, 0x20000
	s_addc_u32 s17, s17, 0
	global_load_dword v39, v2, s[16:17]
	s_add_u32 s16, s16, 0x20000
	s_addc_u32 s17, s17, 0
	s_load_dword s56, s[24:25], 0x0
	s_load_dword s57, s[24:25], 0x20
	s_load_dword s58, s[24:25], 0x40
	s_load_dword s59, s[24:25], 0x60
	s_load_dword s60, s[24:25], 0x80
	s_load_dword s61, s[24:25], 0xa0
	s_load_dword s62, s[24:25], 0xc0
	s_load_dword s63, s[24:25], 0xe0
	s_add_u32 s24, s24, 0x100
	s_addc_u32 s25, s25, 0
	s_mov_b32 s22, 6
.Lp3_ssd_loop:
	s_waitcnt vmcnt(48) lgkmcnt(0)
	v_cvt_pk_bf16_f32 v6, v4, v5
	global_store_dword v2, v6, s[18:19]
	s_add_u32 s18, s18, 0x20000
	s_addc_u32 s19, s19, 0
	v_lshlrev_b32_e32 v40, 16, v8
	v_and_b32_e32 v41, 0xffff0000, v8
	v_fma_f32 v4, v4, s32, v40
	v_fma_f32 v5, v5, s32, v41
	v_cvt_pk_bf16_f32 v6, v4, v5
	global_store_dword v2, v6, s[18:19]
	s_add_u32 s18, s18, 0x20000
	s_addc_u32 s19, s19, 0
	v_lshlrev_b32_e32 v40, 16, v9
	v_and_b32_e32 v41, 0xffff0000, v9
	v_fma_f32 v4, v4, s33, v40
	v_fma_f32 v5, v5, s33, v41
	v_cvt_pk_bf16_f32 v6, v4, v5
	global_store_dword v2, v6, s[18:19]
	s_add_u32 s18, s18, 0x20000
	s_addc_u32 s19, s19, 0
	v_lshlrev_b32_e32 v40, 16, v10
	v_and_b32_e32 v41, 0xffff0000, v10
	v_fma_f32 v4, v4, s34, v40
	v_fma_f32 v5, v5, s34, v41
	v_cvt_pk_bf16_f32 v6, v4, v5
	global_store_dword v2, v6, s[18:19]
	s_add_u32 s18, s18, 0x20000
	s_addc_u32 s19, s19, 0
	v_lshlrev_b32_e32 v40, 16, v11
	v_and_b32_e32 v41, 0xffff0000, v11
	v_fma_f32 v4, v4, s35, v40
	v_fma_f32 v5, v5, s35, v41
	v_cvt_pk_bf16_f32 v6, v4, v5
	global_store_dword v2, v6, s[18:19]
	s_add_u32 s18, s18, 0x20000
	s_addc_u32 s19, s19, 0
	v_lshlrev_b32_e32 v40, 16, v12
	v_and_b32_e32 v41, 0xffff0000, v12
	v_fma_f32 v4, v4, s36, v40
	v_fma_f32 v5, v5, s36, v41
	v_cvt_pk_bf16_f32 v6, v4, v5
	global_store_dword v2, v6, s[18:19]
	s_add_u32 s18, s18, 0x20000
	s_addc_u32 s19, s19, 0
	v_lshlrev_b32_e32 v40, 16, v13
	v_and_b32_e32 v41, 0xffff0000, v13
	v_fma_f32 v4, v4, s37, v40
	v_fma_f32 v5, v5, s37, v41
	v_cvt_pk_bf16_f32 v6, v4, v5
	global_store_dword v2, v6, s[18:19]
	s_add_u32 s18, s18, 0x20000
	s_addc_u32 s19, s19, 0
	v_lshlrev_b32_e32 v40, 16, v14
	v_and_b32_e32 v41, 0xffff0000, v14
	v_fma_f32 v4, v4, s38, v40
	v_fma_f32 v5, v5, s38, v41
	v_cvt_pk_bf16_f32 v6, v4, v5
	global_store_dword v2, v6, s[18:19]
	s_add_u32 s18, s18, 0x20000
	s_addc_u32 s19, s19, 0
	v_lshlrev_b32_e32 v40, 16, v15
	v_and_b32_e32 v41, 0xffff0000, v15
	v_fma_f32 v4, v4, s39, v40
	v_fma_f32 v5, v5, s39, v41
	global_load_dword v8, v2, s[16:17]
	s_add_u32 s16, s16, 0x20000
	s_addc_u32 s17, s17, 0
	global_load_dword v9, v2, s[16:17]
	s_add_u32 s16, s16, 0x20000
	s_addc_u32 s17, s17, 0
	global_load_dword v10, v2, s[16:17]
	s_add_u32 s16, s16, 0x20000
	s_addc_u32 s17, s17, 0
	global_load_dword v11, v2, s[16:17]
	s_add_u32 s16, s16, 0x20000
	s_addc_u32 s17, s17, 0
	global_load_dword v12, v2, s[16:17]
	s_add_u32 s16, s16, 0x20000
	s_addc_u32 s17, s17, 0
	global_load_dword v13, v2, s[16:17]
	s_add_u32 s16, s16, 0x20000
	s_addc_u32 s17, s17, 0
	global_load_dword v14, v2, s[16:17]
	s_add_u32 s16, s16, 0x20000
	s_addc_u32 s17, s17, 0
	global_load_dword v15, v2, s[16:17]
	s_add_u32 s16, s16, 0x20000
	s_addc_u32 s17, s17, 0
	s_load_dword s32, s[24:25], 0x0
	s_load_dword s33, s[24:25], 0x20
	s_load_dword s34, s[24:25], 0x40
	s_load_dword s35, s[24:25], 0x60
	s_load_dword s36, s[24:25], 0x80
	s_load_dword s37, s[24:25], 0xa0
	s_load_dword s38, s[24:25], 0xc0
	s_load_dword s39, s[24:25], 0xe0
	s_add_u32 s24, s24, 0x100
	s_addc_u32 s25, s25, 0
	s_waitcnt vmcnt(48) lgkmcnt(0)
	v_cvt_pk_bf16_f32 v6, v4, v5
	global_store_dword v2, v6, s[18:19]
	s_add_u32 s18, s18, 0x20000
	s_addc_u32 s19, s19, 0
	v_lshlrev_b32_e32 v40, 16, v16
	v_and_b32_e32 v41, 0xffff0000, v16
	v_fma_f32 v4, v4, s40, v40
	v_fma_f32 v5, v5, s40, v41
	v_cvt_pk_bf16_f32 v6, v4, v5
	global_store_dword v2, v6, s[18:19]
	s_add_u32 s18, s18, 0x20000
	s_addc_u32 s19, s19, 0
	v_lshlrev_b32_e32 v40, 16, v17
	v_and_b32_e32 v41, 0xffff0000, v17
	v_fma_f32 v4, v4, s41, v40
	v_fma_f32 v5, v5, s41, v41
	v_cvt_pk_bf16_f32 v6, v4, v5
	global_store_dword v2, v6, s[18:19]
	s_add_u32 s18, s18, 0x20000
	s_addc_u32 s19, s19, 0
	v_lshlrev_b32_e32 v40, 16, v18
	v_and_b32_e32 v41, 0xffff0000, v18
	v_fma_f32 v4, v4, s42, v40
	v_fma_f32 v5, v5, s42, v41
	v_cvt_pk_bf16_f32 v6, v4, v5
	global_store_dword v2, v6, s[18:19]
	s_add_u32 s18, s18, 0x20000
	s_addc_u32 s19, s19, 0
	v_lshlrev_b32_e32 v40, 16, v19
	v_and_b32_e32 v41, 0xffff0000, v19
	v_fma_f32 v4, v4, s43, v40
	v_fma_f32 v5, v5, s43, v41
	v_cvt_pk_bf16_f32 v6, v4, v5
	global_store_dword v2, v6, s[18:19]
	s_add_u32 s18, s18, 0x20000
	s_addc_u32 s19, s19, 0
	v_lshlrev_b32_e32 v40, 16, v20
	v_and_b32_e32 v41, 0xffff0000, v20
	v_fma_f32 v4, v4, s44, v40
	v_fma_f32 v5, v5, s44, v41
	v_cvt_pk_bf16_f32 v6, v4, v5
	global_store_dword v2, v6, s[18:19]
	s_add_u32 s18, s18, 0x20000
	s_addc_u32 s19, s19, 0
	v_lshlrev_b32_e32 v40, 16, v21
	v_and_b32_e32 v41, 0xffff0000, v21
	v_fma_f32 v4, v4, s45, v40
	v_fma_f32 v5, v5, s45, v41
	v_cvt_pk_bf16_f32 v6, v4, v5
	global_store_dword v2, v6, s[18:19]
	s_add_u32 s18, s18, 0x20000
	s_addc_u32 s19, s19, 0
	v_lshlrev_b32_e32 v40, 16, v22
	v_and_b32_e32 v41, 0xffff0000, v22
	v_fma_f32 v4, v4, s46, v40
	v_fma_f32 v5, v5, s46, v41
	v_cvt_pk_bf16_f32 v6, v4, v5
	global_store_dword v2, v6, s[18:19]
	s_add_u32 s18, s18, 0x20000
	s_addc_u32 s19, s19, 0
	v_lshlrev_b32_e32 v40, 16, v23
	v_and_b32_e32 v41, 0xffff0000, v23
	v_fma_f32 v4, v4, s47, v40
	v_fma_f32 v5, v5, s47, v41
	global_load_dword v16, v2, s[16:17]
	s_add_u32 s16, s16, 0x20000
	s_addc_u32 s17, s17, 0
	global_load_dword v17, v2, s[16:17]
	s_add_u32 s16, s16, 0x20000
	s_addc_u32 s17, s17, 0
	global_load_dword v18, v2, s[16:17]
	s_add_u32 s16, s16, 0x20000
	s_addc_u32 s17, s17, 0
	global_load_dword v19, v2, s[16:17]
	s_add_u32 s16, s16, 0x20000
	s_addc_u32 s17, s17, 0
	global_load_dword v20, v2, s[16:17]
	s_add_u32 s16, s16, 0x20000
	s_addc_u32 s17, s17, 0
	global_load_dword v21, v2, s[16:17]
	s_add_u32 s16, s16, 0x20000
	s_addc_u32 s17, s17, 0
	global_load_dword v22, v2, s[16:17]
	s_add_u32 s16, s16, 0x20000
	s_addc_u32 s17, s17, 0
	global_load_dword v23, v2, s[16:17]
	s_add_u32 s16, s16, 0x20000
	s_addc_u32 s17, s17, 0
	s_load_dword s40, s[24:25], 0x0
	s_load_dword s41, s[24:25], 0x20
	s_load_dword s42, s[24:25], 0x40
	s_load_dword s43, s[24:25], 0x60
	s_load_dword s44, s[24:25], 0x80
	s_load_dword s45, s[24:25], 0xa0
	s_load_dword s46, s[24:25], 0xc0
	s_load_dword s47, s[24:25], 0xe0
	s_add_u32 s24, s24, 0x100
	s_addc_u32 s25, s25, 0
	s_waitcnt vmcnt(48) lgkmcnt(0)
	v_cvt_pk_bf16_f32 v6, v4, v5
	global_store_dword v2, v6, s[18:19]
	s_add_u32 s18, s18, 0x20000
	s_addc_u32 s19, s19, 0
	v_lshlrev_b32_e32 v40, 16, v24
	v_and_b32_e32 v41, 0xffff0000, v24
	v_fma_f32 v4, v4, s48, v40
	v_fma_f32 v5, v5, s48, v41
	v_cvt_pk_bf16_f32 v6, v4, v5
	global_store_dword v2, v6, s[18:19]
	s_add_u32 s18, s18, 0x20000
	s_addc_u32 s19, s19, 0
	v_lshlrev_b32_e32 v40, 16, v25
	v_and_b32_e32 v41, 0xffff0000, v25
	v_fma_f32 v4, v4, s49, v40
	v_fma_f32 v5, v5, s49, v41
	v_cvt_pk_bf16_f32 v6, v4, v5
	global_store_dword v2, v6, s[18:19]
	s_add_u32 s18, s18, 0x20000
	s_addc_u32 s19, s19, 0
	v_lshlrev_b32_e32 v40, 16, v26
	v_and_b32_e32 v41, 0xffff0000, v26
	v_fma_f32 v4, v4, s50, v40
	v_fma_f32 v5, v5, s50, v41
	v_cvt_pk_bf16_f32 v6, v4, v5
	global_store_dword v2, v6, s[18:19]
	s_add_u32 s18, s18, 0x20000
	s_addc_u32 s19, s19, 0
	v_lshlrev_b32_e32 v40, 16, v27
	v_and_b32_e32 v41, 0xffff0000, v27
	v_fma_f32 v4, v4, s51, v40
	v_fma_f32 v5, v5, s51, v41
	v_cvt_pk_bf16_f32 v6, v4, v5
	global_store_dword v2, v6, s[18:19]
	s_add_u32 s18, s18, 0x20000
	s_addc_u32 s19, s19, 0
	v_lshlrev_b32_e32 v40, 16, v28
	v_and_b32_e32 v41, 0xffff0000, v28
	v_fma_f32 v4, v4, s52, v40
	v_fma_f32 v5, v5, s52, v41
	v_cvt_pk_bf16_f32 v6, v4, v5
	global_store_dword v2, v6, s[18:19]
	s_add_u32 s18, s18, 0x20000
	s_addc_u32 s19, s19, 0
	v_lshlrev_b32_e32 v40, 16, v29
	v_and_b32_e32 v41, 0xffff0000, v29
	v_fma_f32 v4, v4, s53, v40
	v_fma_f32 v5, v5, s53, v41
	v_cvt_pk_bf16_f32 v6, v4, v5
	global_store_dword v2, v6, s[18:19]
	s_add_u32 s18, s18, 0x20000
	s_addc_u32 s19, s19, 0
	v_lshlrev_b32_e32 v40, 16, v30
	v_and_b32_e32 v41, 0xffff0000, v30
	v_fma_f32 v4, v4, s54, v40
	v_fma_f32 v5, v5, s54, v41
	v_cvt_pk_bf16_f32 v6, v4, v5
	global_store_dword v2, v6, s[18:19]
	s_add_u32 s18, s18, 0x20000
	s_addc_u32 s19, s19, 0
	v_lshlrev_b32_e32 v40, 16, v31
	v_and_b32_e32 v41, 0xffff0000, v31
	v_fma_f32 v4, v4, s55, v40
	v_fma_f32 v5, v5, s55, v41
	global_load_dword v24, v2, s[16:17]
	s_add_u32 s16, s16, 0x20000
	s_addc_u32 s17, s17, 0
	global_load_dword v25, v2, s[16:17]
	s_add_u32 s16, s16, 0x20000
	s_addc_u32 s17, s17, 0
	global_load_dword v26, v2, s[16:17]
	s_add_u32 s16, s16, 0x20000
	s_addc_u32 s17, s17, 0
	global_load_dword v27, v2, s[16:17]
	s_add_u32 s16, s16, 0x20000
	s_addc_u32 s17, s17, 0
	global_load_dword v28, v2, s[16:17]
	s_add_u32 s16, s16, 0x20000
	s_addc_u32 s17, s17, 0
	global_load_dword v29, v2, s[16:17]
	s_add_u32 s16, s16, 0x20000
	s_addc_u32 s17, s17, 0
	global_load_dword v30, v2, s[16:17]
	s_add_u32 s16, s16, 0x20000
	s_addc_u32 s17, s17, 0
	global_load_dword v31, v2, s[16:17]
	s_add_u32 s16, s16, 0x20000
	s_addc_u32 s17, s17, 0
	s_load_dword s48, s[24:25], 0x0
	s_load_dword s49, s[24:25], 0x20
	s_load_dword s50, s[24:25], 0x40
	s_load_dword s51, s[24:25], 0x60
	s_load_dword s52, s[24:25], 0x80
	s_load_dword s53, s[24:25], 0xa0
	s_load_dword s54, s[24:25], 0xc0
	s_load_dword s55, s[24:25], 0xe0
	s_add_u32 s24, s24, 0x100
	s_addc_u32 s25, s25, 0
	s_waitcnt vmcnt(48) lgkmcnt(0)
	v_cvt_pk_bf16_f32 v6, v4, v5
	global_store_dword v2, v6, s[18:19]
	s_add_u32 s18, s18, 0x20000
	s_addc_u32 s19, s19, 0
	v_lshlrev_b32_e32 v40, 16, v32
	v_and_b32_e32 v41, 0xffff0000, v32
	v_fma_f32 v4, v4, s56, v40
	v_fma_f32 v5, v5, s56, v41
	v_cvt_pk_bf16_f32 v6, v4, v5
	global_store_dword v2, v6, s[18:19]
	s_add_u32 s18, s18, 0x20000
	s_addc_u32 s19, s19, 0
	v_lshlrev_b32_e32 v40, 16, v33
	v_and_b32_e32 v41, 0xffff0000, v33
	v_fma_f32 v4, v4, s57, v40
	v_fma_f32 v5, v5, s57, v41
	v_cvt_pk_bf16_f32 v6, v4, v5
	global_store_dword v2, v6, s[18:19]
	s_add_u32 s18, s18, 0x20000
	s_addc_u32 s19, s19, 0
	v_lshlrev_b32_e32 v40, 16, v34
	v_and_b32_e32 v41, 0xffff0000, v34
	v_fma_f32 v4, v4, s58, v40
	v_fma_f32 v5, v5, s58, v41
	v_cvt_pk_bf16_f32 v6, v4, v5
	global_store_dword v2, v6, s[18:19]
	s_add_u32 s18, s18, 0x20000
	s_addc_u32 s19, s19, 0
	v_lshlrev_b32_e32 v40, 16, v35
	v_and_b32_e32 v41, 0xffff0000, v35
	v_fma_f32 v4, v4, s59, v40
	v_fma_f32 v5, v5, s59, v41
	v_cvt_pk_bf16_f32 v6, v4, v5
	global_store_dword v2, v6, s[18:19]
	s_add_u32 s18, s18, 0x20000
	s_addc_u32 s19, s19, 0
	v_lshlrev_b32_e32 v40, 16, v36
	v_and_b32_e32 v41, 0xffff0000, v36
	v_fma_f32 v4, v4, s60, v40
	v_fma_f32 v5, v5, s60, v41
	v_cvt_pk_bf16_f32 v6, v4, v5
	global_store_dword v2, v6, s[18:19]
	s_add_u32 s18, s18, 0x20000
	s_addc_u32 s19, s19, 0
	v_lshlrev_b32_e32 v40, 16, v37
	v_and_b32_e32 v41, 0xffff0000, v37
	v_fma_f32 v4, v4, s61, v40
	v_fma_f32 v5, v5, s61, v41
	v_cvt_pk_bf16_f32 v6, v4, v5
	global_store_dword v2, v6, s[18:19]
	s_add_u32 s18, s18, 0x20000
	s_addc_u32 s19, s19, 0
	v_lshlrev_b32_e32 v40, 16, v38
	v_and_b32_e32 v41, 0xffff0000, v38
	v_fma_f32 v4, v4, s62, v40
	v_fma_f32 v5, v5, s62, v41
	v_cvt_pk_bf16_f32 v6, v4, v5
	global_store_dword v2, v6, s[18:19]
	s_add_u32 s18, s18, 0x20000
	s_addc_u32 s19, s19, 0
	v_lshlrev_b32_e32 v40, 16, v39
	v_and_b32_e32 v41, 0xffff0000, v39
	v_fma_f32 v4, v4, s63, v40
	v_fma_f32 v5, v5, s63, v41
	global_load_dword v32, v2, s[16:17]
	s_add_u32 s16, s16, 0x20000
	s_addc_u32 s17, s17, 0
	global_load_dword v33, v2, s[16:17]
	s_add_u32 s16, s16, 0x20000
	s_addc_u32 s17, s17, 0
	global_load_dword v34, v2, s[16:17]
	s_add_u32 s16, s16, 0x20000
	s_addc_u32 s17, s17, 0
	global_load_dword v35, v2, s[16:17]
	s_add_u32 s16, s16, 0x20000
	s_addc_u32 s17, s17, 0
	global_load_dword v36, v2, s[16:17]
	s_add_u32 s16, s16, 0x20000
	s_addc_u32 s17, s17, 0
	global_load_dword v37, v2, s[16:17]
	s_add_u32 s16, s16, 0x20000
	s_addc_u32 s17, s17, 0
	global_load_dword v38, v2, s[16:17]
	s_add_u32 s16, s16, 0x20000
	s_addc_u32 s17, s17, 0
	global_load_dword v39, v2, s[16:17]
	s_add_u32 s16, s16, 0x20000
	s_addc_u32 s17, s17, 0
	s_load_dword s56, s[24:25], 0x0
	s_load_dword s57, s[24:25], 0x20
	s_load_dword s58, s[24:25], 0x40
	s_load_dword s59, s[24:25], 0x60
	s_load_dword s60, s[24:25], 0x80
	s_load_dword s61, s[24:25], 0xa0
	s_load_dword s62, s[24:25], 0xc0
	s_load_dword s63, s[24:25], 0xe0
	s_add_u32 s24, s24, 0x100
	s_addc_u32 s25, s25, 0
	s_sub_u32 s22, s22, 1
	s_cmp_lg_u32 s22, 0
	s_cbranch_scc1 .Lp3_ssd_loop
	s_waitcnt vmcnt(48) lgkmcnt(0)
	v_cvt_pk_bf16_f32 v6, v4, v5
	global_store_dword v2, v6, s[18:19]
	s_add_u32 s18, s18, 0x20000
	s_addc_u32 s19, s19, 0
	v_lshlrev_b32_e32 v40, 16, v8
	v_and_b32_e32 v41, 0xffff0000, v8
	v_fma_f32 v4, v4, s32, v40
	v_fma_f32 v5, v5, s32, v41
	v_cvt_pk_bf16_f32 v6, v4, v5
	global_store_dword v2, v6, s[18:19]
	s_add_u32 s18, s18, 0x20000
	s_addc_u32 s19, s19, 0
	v_lshlrev_b32_e32 v40, 16, v9
	v_and_b32_e32 v41, 0xffff0000, v9
	v_fma_f32 v4, v4, s33, v40
	v_fma_f32 v5, v5, s33, v41
	v_cvt_pk_bf16_f32 v6, v4, v5
	global_store_dword v2, v6, s[18:19]
	s_add_u32 s18, s18, 0x20000
	s_addc_u32 s19, s19, 0
	v_lshlrev_b32_e32 v40, 16, v10
	v_and_b32_e32 v41, 0xffff0000, v10
	v_fma_f32 v4, v4, s34, v40
	v_fma_f32 v5, v5, s34, v41
	v_cvt_pk_bf16_f32 v6, v4, v5
	global_store_dword v2, v6, s[18:19]
	s_add_u32 s18, s18, 0x20000
	s_addc_u32 s19, s19, 0
	v_lshlrev_b32_e32 v40, 16, v11
	v_and_b32_e32 v41, 0xffff0000, v11
	v_fma_f32 v4, v4, s35, v40
	v_fma_f32 v5, v5, s35, v41
	v_cvt_pk_bf16_f32 v6, v4, v5
	global_store_dword v2, v6, s[18:19]
	s_add_u32 s18, s18, 0x20000
	s_addc_u32 s19, s19, 0
	v_lshlrev_b32_e32 v40, 16, v12
	v_and_b32_e32 v41, 0xffff0000, v12
	v_fma_f32 v4, v4, s36, v40
	v_fma_f32 v5, v5, s36, v41
	v_cvt_pk_bf16_f32 v6, v4, v5
	global_store_dword v2, v6, s[18:19]
	s_add_u32 s18, s18, 0x20000
	s_addc_u32 s19, s19, 0
	v_lshlrev_b32_e32 v40, 16, v13
	v_and_b32_e32 v41, 0xffff0000, v13
	v_fma_f32 v4, v4, s37, v40
	v_fma_f32 v5, v5, s37, v41
	v_cvt_pk_bf16_f32 v6, v4, v5
	global_store_dword v2, v6, s[18:19]
	s_add_u32 s18, s18, 0x20000
	s_addc_u32 s19, s19, 0
	v_lshlrev_b32_e32 v40, 16, v14
	v_and_b32_e32 v41, 0xffff0000, v14
	v_fma_f32 v4, v4, s38, v40
	v_fma_f32 v5, v5, s38, v41
	v_cvt_pk_bf16_f32 v6, v4, v5
	global_store_dword v2, v6, s[18:19]
	s_add_u32 s18, s18, 0x20000
	s_addc_u32 s19, s19, 0
	v_lshlrev_b32_e32 v40, 16, v15
	v_and_b32_e32 v41, 0xffff0000, v15
	v_fma_f32 v4, v4, s39, v40
	v_fma_f32 v5, v5, s39, v41
	s_waitcnt vmcnt(40) lgkmcnt(0)
	v_cvt_pk_bf16_f32 v6, v4, v5
	global_store_dword v2, v6, s[18:19]
	s_add_u32 s18, s18, 0x20000
	s_addc_u32 s19, s19, 0
	v_lshlrev_b32_e32 v40, 16, v16
	v_and_b32_e32 v41, 0xffff0000, v16
	v_fma_f32 v4, v4, s40, v40
	v_fma_f32 v5, v5, s40, v41
	v_cvt_pk_bf16_f32 v6, v4, v5
	global_store_dword v2, v6, s[18:19]
	s_add_u32 s18, s18, 0x20000
	s_addc_u32 s19, s19, 0
	v_lshlrev_b32_e32 v40, 16, v17
	v_and_b32_e32 v41, 0xffff0000, v17
	v_fma_f32 v4, v4, s41, v40
	v_fma_f32 v5, v5, s41, v41
	v_cvt_pk_bf16_f32 v6, v4, v5
	global_store_dword v2, v6, s[18:19]
	s_add_u32 s18, s18, 0x20000
	s_addc_u32 s19, s19, 0
	v_lshlrev_b32_e32 v40, 16, v18
	v_and_b32_e32 v41, 0xffff0000, v18
	v_fma_f32 v4, v4, s42, v40
	v_fma_f32 v5, v5, s42, v41
	v_cvt_pk_bf16_f32 v6, v4, v5
	global_store_dword v2, v6, s[18:19]
	s_add_u32 s18, s18, 0x20000
	s_addc_u32 s19, s19, 0
	v_lshlrev_b32_e32 v40, 16, v19
	v_and_b32_e32 v41, 0xffff0000, v19
	v_fma_f32 v4, v4, s43, v40
	v_fma_f32 v5, v5, s43, v41
	v_cvt_pk_bf16_f32 v6, v4, v5
	global_store_dword v2, v6, s[18:19]
	s_add_u32 s18, s18, 0x20000
	s_addc_u32 s19, s19, 0
	v_lshlrev_b32_e32 v40, 16, v20
	v_and_b32_e32 v41, 0xffff0000, v20
	v_fma_f32 v4, v4, s44, v40
	v_fma_f32 v5, v5, s44, v41
	v_cvt_pk_bf16_f32 v6, v4, v5
	global_store_dword v2, v6, s[18:19]
	s_add_u32 s18, s18, 0x20000
	s_addc_u32 s19, s19, 0
	v_lshlrev_b32_e32 v40, 16, v21
	v_and_b32_e32 v41, 0xffff0000, v21
	v_fma_f32 v4, v4, s45, v40
	v_fma_f32 v5, v5, s45, v41
	v_cvt_pk_bf16_f32 v6, v4, v5
	global_store_dword v2, v6, s[18:19]
	s_add_u32 s18, s18, 0x20000
	s_addc_u32 s19, s19, 0
	v_lshlrev_b32_e32 v40, 16, v22
	v_and_b32_e32 v41, 0xffff0000, v22
	v_fma_f32 v4, v4, s46, v40
	v_fma_f32 v5, v5, s46, v41
	v_cvt_pk_bf16_f32 v6, v4, v5
	global_store_dword v2, v6, s[18:19]
	s_add_u32 s18, s18, 0x20000
	s_addc_u32 s19, s19, 0
	v_lshlrev_b32_e32 v40, 16, v23
	v_and_b32_e32 v41, 0xffff0000, v23
	v_fma_f32 v4, v4, s47, v40
	v_fma_f32 v5, v5, s47, v41
	s_waitcnt vmcnt(32) lgkmcnt(0)
	v_cvt_pk_bf16_f32 v6, v4, v5
	global_store_dword v2, v6, s[18:19]
	s_add_u32 s18, s18, 0x20000
	s_addc_u32 s19, s19, 0
	v_lshlrev_b32_e32 v40, 16, v24
	v_and_b32_e32 v41, 0xffff0000, v24
	v_fma_f32 v4, v4, s48, v40
	v_fma_f32 v5, v5, s48, v41
	v_cvt_pk_bf16_f32 v6, v4, v5
	global_store_dword v2, v6, s[18:19]
	s_add_u32 s18, s18, 0x20000
	s_addc_u32 s19, s19, 0
	v_lshlrev_b32_e32 v40, 16, v25
	v_and_b32_e32 v41, 0xffff0000, v25
	v_fma_f32 v4, v4, s49, v40
	v_fma_f32 v5, v5, s49, v41
	v_cvt_pk_bf16_f32 v6, v4, v5
	global_store_dword v2, v6, s[18:19]
	s_add_u32 s18, s18, 0x20000
	s_addc_u32 s19, s19, 0
	v_lshlrev_b32_e32 v40, 16, v26
	v_and_b32_e32 v41, 0xffff0000, v26
	v_fma_f32 v4, v4, s50, v40
	v_fma_f32 v5, v5, s50, v41
	v_cvt_pk_bf16_f32 v6, v4, v5
	global_store_dword v2, v6, s[18:19]
	s_add_u32 s18, s18, 0x20000
	s_addc_u32 s19, s19, 0
	v_lshlrev_b32_e32 v40, 16, v27
	v_and_b32_e32 v41, 0xffff0000, v27
	v_fma_f32 v4, v4, s51, v40
	v_fma_f32 v5, v5, s51, v41
	v_cvt_pk_bf16_f32 v6, v4, v5
	global_store_dword v2, v6, s[18:19]
	s_add_u32 s18, s18, 0x20000
	s_addc_u32 s19, s19, 0
	v_lshlrev_b32_e32 v40, 16, v28
	v_and_b32_e32 v41, 0xffff0000, v28
	v_fma_f32 v4, v4, s52, v40
	v_fma_f32 v5, v5, s52, v41
	v_cvt_pk_bf16_f32 v6, v4, v5
	global_store_dword v2, v6, s[18:19]
	s_add_u32 s18, s18, 0x20000
	s_addc_u32 s19, s19, 0
	v_lshlrev_b32_e32 v40, 16, v29
	v_and_b32_e32 v41, 0xffff0000, v29
	v_fma_f32 v4, v4, s53, v40
	v_fma_f32 v5, v5, s53, v41
	v_cvt_pk_bf16_f32 v6, v4, v5
	global_store_dword v2, v6, s[18:19]
	s_add_u32 s18, s18, 0x20000
	s_addc_u32 s19, s19, 0
	v_lshlrev_b32_e32 v40, 16, v30
	v_and_b32_e32 v41, 0xffff0000, v30
	v_fma_f32 v4, v4, s54, v40
	v_fma_f32 v5, v5, s54, v41
	v_cvt_pk_bf16_f32 v6, v4, v5
	global_store_dword v2, v6, s[18:19]
	s_add_u32 s18, s18, 0x20000
	s_addc_u32 s19, s19, 0
	v_lshlrev_b32_e32 v40, 16, v31
	v_and_b32_e32 v41, 0xffff0000, v31
	v_fma_f32 v4, v4, s55, v40
	v_fma_f32 v5, v5, s55, v41
	s_waitcnt vmcnt(24) lgkmcnt(0)
	v_cvt_pk_bf16_f32 v6, v4, v5
	global_store_dword v2, v6, s[18:19]
	s_add_u32 s18, s18, 0x20000
	s_addc_u32 s19, s19, 0
	v_lshlrev_b32_e32 v40, 16, v32
	v_and_b32_e32 v41, 0xffff0000, v32
	v_fma_f32 v4, v4, s56, v40
	v_fma_f32 v5, v5, s56, v41
	v_cvt_pk_bf16_f32 v6, v4, v5
	global_store_dword v2, v6, s[18:19]
	s_add_u32 s18, s18, 0x20000
	s_addc_u32 s19, s19, 0
	v_lshlrev_b32_e32 v40, 16, v33
	v_and_b32_e32 v41, 0xffff0000, v33
	v_fma_f32 v4, v4, s57, v40
	v_fma_f32 v5, v5, s57, v41
	v_cvt_pk_bf16_f32 v6, v4, v5
	global_store_dword v2, v6, s[18:19]
	s_add_u32 s18, s18, 0x20000
	s_addc_u32 s19, s19, 0
	v_lshlrev_b32_e32 v40, 16, v34
	v_and_b32_e32 v41, 0xffff0000, v34
	v_fma_f32 v4, v4, s58, v40
	v_fma_f32 v5, v5, s58, v41
	v_cvt_pk_bf16_f32 v6, v4, v5
	global_store_dword v2, v6, s[18:19]
	s_add_u32 s18, s18, 0x20000
	s_addc_u32 s19, s19, 0
	v_lshlrev_b32_e32 v40, 16, v35
	v_and_b32_e32 v41, 0xffff0000, v35
	v_fma_f32 v4, v4, s59, v40
	v_fma_f32 v5, v5, s59, v41
	v_cvt_pk_bf16_f32 v6, v4, v5
	global_store_dword v2, v6, s[18:19]
	s_add_u32 s18, s18, 0x20000
	s_addc_u32 s19, s19, 0
	v_lshlrev_b32_e32 v40, 16, v36
	v_and_b32_e32 v41, 0xffff0000, v36
	v_fma_f32 v4, v4, s60, v40
	v_fma_f32 v5, v5, s60, v41
	v_cvt_pk_bf16_f32 v6, v4, v5
	global_store_dword v2, v6, s[18:19]
	s_add_u32 s18, s18, 0x20000
	s_addc_u32 s19, s19, 0
	v_lshlrev_b32_e32 v40, 16, v37
	v_and_b32_e32 v41, 0xffff0000, v37
	v_fma_f32 v4, v4, s61, v40
	v_fma_f32 v5, v5, s61, v41
	v_cvt_pk_bf16_f32 v6, v4, v5
	global_store_dword v2, v6, s[18:19]
	s_add_u32 s18, s18, 0x20000
	s_addc_u32 s19, s19, 0
	v_lshlrev_b32_e32 v40, 16, v38
	v_and_b32_e32 v41, 0xffff0000, v38
	v_fma_f32 v4, v4, s62, v40
	v_fma_f32 v5, v5, s62, v41
	v_cvt_pk_bf16_f32 v6, v4, v5
	global_store_dword v2, v6, s[18:19]
	s_add_u32 s18, s18, 0x20000
	s_addc_u32 s19, s19, 0
	v_lshlrev_b32_e32 v40, 16, v39
	v_and_b32_e32 v41, 0xffff0000, v39
	v_fma_f32 v4, v4, s63, v40
	v_fma_f32 v5, v5, s63, v41
.Lp3_done:
.LBB0_585:
	s_or_b64 exec, exec, s[6:7]
	v_readlane_b32 s0, v253, 4
	s_cmp_eq_u32 s0, 4
	s_cbranch_scc1 .LBB0_638
	s_waitcnt vmcnt(0)
	s_waitcnt vmcnt(0) lgkmcnt(0)
	s_barrier
	s_mov_b64 s[4:5], exec
	v_readlane_b32 s0, v253, 2
	v_readlane_b32 s1, v253, 3
	s_and_b64 s[0:1], s[4:5], s[0:1]
	s_mov_b64 exec, s[0:1]
	s_cbranch_execz .LBB0_637
	s_add_i32 s0, 0, 0x23ff0
	v_mov_b32_e32 v0, s0
	s_waitcnt vmcnt(0) expcnt(0) lgkmcnt(0)
	ds_read_b32 v2, v0
	s_add_i32 s0, 0, 0x23ff4
	v_mov_b32_e32 v0, s0
	ds_read_b32 v0, v0
	s_waitcnt lgkmcnt(1)
	v_cmp_ne_u32_e32 vcc, 0, v2
	s_cbranch_vccnz .LBB0_602
	v_readlane_b32 s6, v253, 0
	v_readlane_b32 s7, v253, 1
	s_load_dwordx2 s[0:1], s[6:7], 0x4
	s_add_u32 s6, s70, 0x1000
	s_addc_u32 s7, s71, 0
	s_add_u32 s8, s70, 0x1100
	s_addc_u32 s9, s71, 0
	s_add_u32 s10, s70, 0x1200
	s_addc_u32 s11, s71, 0
	s_waitcnt lgkmcnt(0)
	s_mul_i32 s18, s0, s90
	s_add_u32 s12, s70, 0x1300
	s_mul_i32 s18, s18, s1
	s_addc_u32 s13, s71, 0
	s_mov_b32 s19, 1
	v_mov_b32_e32 v16, 0
	s_branch .LBB0_590
